# GEMM accumulators zeroed by 7 zero-operand MFMAs instead of 112 v_mov per unit
# speedup vs baseline: 1.0419x; 1.0110x over previous
.LBB0_192:
	s_ashr_i32 s23, s22, 31
	s_lshl_b64 s[24:25], s[22:23], 19
	s_add_u32 s24, s3, s24
	s_addc_u32 s25, s33, s25
	s_and_b64 s[26:27], s[0:1], exec
	s_cselect_b32 s23, s25, s5
	s_cselect_b32 s38, s24, s4
	s_ashr_i32 s21, s20, 31
	s_lshl_b64 s[26:27], s[20:21], 19
	s_add_u32 s26, s40, s26
	s_addc_u32 s27, s41, s27
	s_and_b64 s[34:35], s[0:1], exec
	s_cselect_b32 s21, s27, s31
	s_cselect_b32 s39, s26, s30
	s_add_u32 s4, s4, 0x40080
	s_addc_u32 s5, s5, 0
	s_add_u32 s52, s30, 0x100
	v_mov_b32_e32 v2, 0
	s_addc_u32 s53, s31, 0
	s_mov_b32 s54, -2
	v_mov_b32_e32 v3, v2
	v_mov_b32_e32 v4, v2
	v_mov_b32_e32 v5, v2
	v_mov_b32_e32 v6, v2
	v_mov_b32_e32 v7, v2
	v_mov_b32_e32 v8, v2
	v_mov_b32_e32 v9, v2
	v_mov_b32_e32 v10, v2
	v_mov_b32_e32 v11, v2
	v_mov_b32_e32 v12, v2
	v_mov_b32_e32 v13, v2
	v_mov_b32_e32 v14, v2
	v_mov_b32_e32 v15, v2
	v_mov_b32_e32 v16, v2
	v_mov_b32_e32 v17, v2
	s_nop 1
	v_mfma_f32_32x32x16_bf16 v[18:33], v[2:5], v[2:5], 0
	v_mfma_f32_32x32x16_bf16 v[34:49], v[2:5], v[2:5], 0
	v_mfma_f32_32x32x16_bf16 v[50:65], v[2:5], v[2:5], 0
	v_mfma_f32_32x32x16_bf16 v[66:81], v[2:5], v[2:5], 0
	v_mfma_f32_32x32x16_bf16 v[82:97], v[2:5], v[2:5], 0
	v_mfma_f32_32x32x16_bf16 v[98:113], v[2:5], v[2:5], 0
	v_mfma_f32_32x32x16_bf16 v[114:129], v[2:5], v[2:5], 0

.LBB0_301:
	s_add_i32 s30, s27, s19
	s_cmpk_gt_i32 s30, 0x1ff
	s_mov_b64 s[12:13], -1
	s_cbranch_scc1 .LBB0_300
	s_ashr_i32 s28, s30, 8
	s_and_b32 s31, s26, 0x80
	s_mul_i32 s13, s28, 0x6000000
	s_mul_hi_i32 s12, s28, 0x6000000
	s_add_u32 s33, s37, s13
	s_addc_u32 s35, s40, s12
	s_lshl_b32 s12, s30, 1
	s_and_b32 s29, s12, 0x1c0
	s_lshl_b32 s12, s29, 1
	s_add_u32 s12, s33, s12
	s_addc_u32 s13, s35, 0
	s_and_b32 s34, s30, 0x80
	s_add_u32 s34, s33, s34
	s_addc_u32 s35, s35, 0
	s_lshl_b32 s30, s30, 9
	v_mov_b32_e32 v14, v0
	s_and_b32 s30, s30, 0x3e00
	v_mov_b32_e32 v11, v171
	v_readfirstlane_b32 s33, v14
	s_andn2_b32 s33, s33, 63
	v_and_or_b32 v2, v14, 31, s30
	v_bfe_u32 v15, v14, 5, 1
	v_add_u32_e32 v172, s33, v2
	v_mov_b64_e32 v[2:3], s[12:13]
	v_mad_i64_i32 v[2:3], s[12:13], v172, s20, v[2:3]
	v_lshlrev_b32_e32 v170, 4, v15
	v_lshl_add_u64 v[2:3], v[2:3], 0, v[170:171]
	v_lshl_add_u64 v[4:5], v[2:3], 0, s[6:7]
	v_add_co_u32_e32 v6, vcc, s21, v2
	v_ashrrev_i32_e32 v16, 3, v14
	s_nop 0
	v_addc_co_u32_e32 v7, vcc, 0, v3, vcc
	global_load_dwordx4 v[130:133], v[2:3], off
	global_load_dwordx4 v[134:137], v[2:3], off offset:32
	global_load_dwordx4 v[138:141], v[4:5], off offset:32
	global_load_dwordx4 v[142:145], v[4:5], off offset:64
	global_load_dwordx4 v[146:149], v[2:3], off offset:64
	global_load_dwordx4 v[150:153], v[2:3], off offset:96
	global_load_dwordx4 v[154:157], v[6:7], off
	global_load_dwordx4 v[158:161], v[4:5], off offset:96
	v_mov_b64_e32 v[2:3], s[34:35]
	v_lshlrev_b32_e32 v4, 4, v14
	v_mad_i64_i32 v[2:3], s[12:13], v16, s20, v[2:3]
	v_and_b32_e32 v10, 0x70, v4
	v_lshl_add_u64 v[12:13], v[2:3], 0, v[10:11]
	global_load_dwordx4 v[2:5], v[12:13], off offset:1024
	global_load_dwordx4 v[6:9], v[12:13], off offset:1280
	v_add_co_u32_e32 v12, vcc, s23, v12
	s_waitcnt lgkmcnt(0)
	s_nop 0
	v_addc_co_u32_e32 v13, vcc, 0, v13, vcc
	s_barrier
	global_load_dwordx4 v[162:165], v[12:13], off offset:1024
	global_load_dwordx4 v[166:169], v[12:13], off offset:1280
	v_lshlrev_b32_e32 v12, 1, v14
	v_lshrrev_b32_e32 v13, 1, v14
	v_lshlrev_b32_e32 v174, 3, v15
	v_and_b32_e32 v15, 8, v12
	v_and_b32_e32 v18, 4, v13
	v_and_b32_e32 v173, 32, v12
	v_mad_i64_i32 v[12:13], s[12:13], v16, s20, 0
	v_and_b32_e32 v11, 19, v14
	v_lshrrev_b32_e32 v17, 2, v14
	v_lshlrev_b32_e32 v14, 3, v14
	v_mul_lo_u32 v19, v16, s22
	v_mad_i64_i32 v[12:13], s[12:13], s28, v1, v[12:13]
	v_mov_b32_e32 v50, 0
	v_and_b32_e32 v175, 24, v14
	v_or3_b32 v11, v11, v15, v18
	v_and_or_b32 v14, v17, 3, v174
	v_add3_u32 v180, 0, v19, v10
	v_or3_b32 v12, v12, s31, v10
	s_mov_b32 s33, 0
	s_mov_b32 s30, 0
	v_mov_b32_e32 v51, v50
	v_mov_b32_e32 v52, v50
	v_mov_b32_e32 v53, v50
	v_mov_b32_e32 v54, v50
	v_mov_b32_e32 v55, v50
	v_mov_b32_e32 v56, v50
	v_mov_b32_e32 v57, v50
	v_mov_b32_e32 v58, v50
	v_mul_u32_u24_e32 v181, 0x90, v11
	v_mul_u32_u24_e32 v182, 0x90, v14
	v_lshl_add_u64 v[176:177], s[4:5], 0, v[12:13]
	v_mov_b32_e32 v59, v50
	v_mov_b32_e32 v60, v50
	v_mov_b32_e32 v61, v50
	v_mov_b32_e32 v62, v50
	v_mov_b32_e32 v63, v50
	v_mov_b32_e32 v64, v50
	v_mov_b32_e32 v65, v50
	v_mov_b32_e32 v34, v50
	v_mov_b32_e32 v35, v50
	v_mov_b32_e32 v36, v50
	v_mov_b32_e32 v37, v50
	v_mov_b32_e32 v38, v50
	v_mov_b32_e32 v39, v50
	v_mov_b32_e32 v40, v50
	v_mov_b32_e32 v41, v50
	v_mov_b32_e32 v42, v50
	v_mov_b32_e32 v43, v50
	s_waitcnt vmcnt(3)
	ds_write_b128 v180, v[2:5]
	s_waitcnt vmcnt(2)
	ds_write_b128 v180, v[6:9] offset:9216
	s_waitcnt vmcnt(1)
	ds_write_b128 v180, v[162:165] offset:18432
	s_waitcnt vmcnt(0)
	ds_write_b128 v180, v[166:169] offset:27648
	v_mov_b32_e32 v44, v50
	v_mov_b32_e32 v45, v50
	v_mov_b32_e32 v46, v50
	v_mov_b32_e32 v47, v50
	v_mov_b32_e32 v48, v50
	v_mov_b32_e32 v49, v50
	v_mov_b32_e32 v2, v50
	v_mov_b32_e32 v3, v50
	v_mov_b32_e32 v4, v50
	v_mov_b32_e32 v5, v50
	v_mov_b32_e32 v6, v50
	v_mov_b32_e32 v7, v50
	v_mov_b32_e32 v8, v50
	v_mov_b32_e32 v9, v50
	v_mov_b32_e32 v10, v50
	v_mov_b32_e32 v11, v50
	v_mov_b32_e32 v12, v50
	v_mov_b32_e32 v13, v50
	v_mov_b32_e32 v14, v50
	v_mov_b32_e32 v15, v50
	v_mov_b32_e32 v16, v50
	v_mov_b32_e32 v17, v50
	v_mov_b32_e32 v18, v50
	v_mov_b32_e32 v19, v50
	v_mov_b32_e32 v20, v50
	v_mov_b32_e32 v21, v50
	v_mov_b32_e32 v22, v50
	v_mov_b32_e32 v23, v50
	v_mov_b32_e32 v24, v50
	v_mov_b32_e32 v25, v50
	v_mov_b32_e32 v26, v50
	v_mov_b32_e32 v27, v50
	v_mov_b32_e32 v28, v50
	v_mov_b32_e32 v29, v50
	v_mov_b32_e32 v30, v50
	v_mov_b32_e32 v31, v50
	v_mov_b32_e32 v32, v50
	v_mov_b32_e32 v33, v50
	v_mov_b32_e32 v178, v50
	v_mov_b32_e32 v179, v50
	v_mov_b32_e32 v218, 0
	v_mov_b32_e32 v219, 0
	v_mov_b32_e32 v220, 0
	v_mov_b32_e32 v221, 0
	v_mov_b32_e32 v222, 0
	v_mov_b32_e32 v223, 0
	v_mov_b32_e32 v208, 0
	v_mov_b32_e32 v209, 0
	v_mov_b32_e32 v210, 0
	v_mov_b32_e32 v211, 0
	v_mov_b32_e32 v212, 0
	v_mov_b32_e32 v213, 0
	v_mov_b32_e32 v214, 0
	v_mov_b32_e32 v215, 0
	v_mov_b32_e32 v106, 0
	v_mov_b32_e32 v107, 0
	v_mov_b32_e32 v108, 0
	v_mov_b32_e32 v109, 0
	v_mov_b32_e32 v122, 0
	v_mov_b32_e32 v123, 0
	v_mov_b32_e32 v124, 0
	v_mov_b32_e32 v125, 0
	s_waitcnt lgkmcnt(0)
	s_barrier
	v_add_u32_e32 v183, v181, v170
	v_add3_u32 v216, v182, v173, v175
	ds_read_b128 v[184:187], v183
	ds_read_b128 v[188:191], v183 offset:32
	ds_read_b128 v[192:195], v183 offset:64
	ds_read_b128 v[196:199], v183 offset:96
	s_waitcnt lgkmcnt(3)
	v_mfma_f32_32x32x16_bf16 v[66:81], v[184:187], v[130:133], 0
	s_waitcnt lgkmcnt(2)
	v_mfma_f32_32x32x16_bf16 v[66:81], v[188:191], v[134:137], v[66:81]
	s_waitcnt lgkmcnt(1)
	v_mfma_f32_32x32x16_bf16 v[66:81], v[192:195], v[146:149], v[66:81]
	s_waitcnt lgkmcnt(0)
	v_mfma_f32_32x32x16_bf16 v[66:81], v[196:199], v[150:153], v[66:81]
	v_mfma_f32_32x32x16_bf16 v[82:97], v[184:187], v[154:157], 0
	v_mfma_f32_32x32x16_bf16 v[82:97], v[188:191], v[138:141], v[82:97]
	v_mfma_f32_32x32x16_bf16 v[82:97], v[192:195], v[142:145], v[82:97]
	v_mfma_f32_32x32x16_bf16 v[82:97], v[196:199], v[158:161], v[82:97]
	s_branch .Lat_enter

.Lat_enter:
	global_load_dwordx4 v[162:165], v[176:177], off
	global_load_dwordx4 v[166:169], v[176:177], off offset:256
	ds_read_b128 v[184:187], v183 offset:4608
	ds_read_b128 v[188:191], v183 offset:4640
	ds_read_b128 v[192:195], v183 offset:4672
	ds_read_b128 v[196:199], v183 offset:4704
	v_exp_f32_e32 v66, v66
	v_exp_f32_e32 v67, v67
	v_add_f32_e32 v178, v178, v66
	v_add_f32_e32 v218, v218, v67
	v_cvt_pk_bf16_f32 v66, v66, v67
	v_mfma_f32_32x32x16_bf16 v[50:65], v[208:211], v[106:109], v[50:65]
	v_exp_f32_e32 v68, v68
	v_exp_f32_e32 v69, v69
	v_add_f32_e32 v219, v219, v68
	v_add_f32_e32 v220, v220, v69
	v_cvt_pk_bf16_f32 v67, v68, v69
	v_mfma_f32_32x32x16_bf16 v[34:49], v[212:215], v[106:109], v[34:49]
	v_lshl_add_u64 v[176:177], v[176:177], 0, s[8:9]
	v_exp_f32_e32 v70, v70
	v_exp_f32_e32 v71, v71
	v_add_f32_e32 v178, v178, v70
	v_add_f32_e32 v218, v218, v71
	v_cvt_pk_bf16_f32 v68, v70, v71
	v_mfma_f32_32x32x16_bf16 v[18:33], v[208:211], v[122:125], v[18:33]
	v_exp_f32_e32 v72, v72
	v_exp_f32_e32 v73, v73
	v_add_f32_e32 v219, v219, v72
	v_add_f32_e32 v220, v220, v73
	v_cvt_pk_bf16_f32 v69, v72, v73
	v_mfma_f32_32x32x16_bf16 v[2:17], v[212:215], v[122:125], v[2:17]
	v_exp_f32_e32 v82, v82
	v_exp_f32_e32 v83, v83
	v_add_f32_e32 v179, v179, v82
	v_add_f32_e32 v221, v221, v83
	v_cvt_pk_bf16_f32 v82, v82, v83
	s_waitcnt lgkmcnt(0)
	v_mfma_f32_32x32x16_bf16 v[98:113], v[184:187], v[130:133], 0
	ds_read_b64_tr_b16 v[200:201], v216 offset:9216
	ds_read_b64_tr_b16 v[202:203], v216 offset:9792
	ds_read_b64_tr_b16 v[204:205], v216 offset:9280
	ds_read_b64_tr_b16 v[206:207], v216 offset:9856
	v_exp_f32_e32 v84, v84
	v_exp_f32_e32 v85, v85
	v_add_f32_e32 v222, v222, v84
	v_add_f32_e32 v223, v223, v85
	v_cvt_pk_bf16_f32 v83, v84, v85
	v_mfma_f32_32x32x16_bf16 v[98:113], v[188:191], v[134:137], v[98:113]
	ds_read_b64_tr_b16 v[208:209], v216 offset:11520
	ds_read_b64_tr_b16 v[210:211], v216 offset:12096
	ds_read_b64_tr_b16 v[212:213], v216 offset:11584
	ds_read_b64_tr_b16 v[214:215], v216 offset:12160
	v_exp_f32_e32 v86, v86
	v_exp_f32_e32 v87, v87
	v_add_f32_e32 v179, v179, v86
	v_add_f32_e32 v221, v221, v87
	v_cvt_pk_bf16_f32 v84, v86, v87
	v_mfma_f32_32x32x16_bf16 v[98:113], v[192:195], v[146:149], v[98:113]
	v_exp_f32_e32 v88, v88
	v_exp_f32_e32 v89, v89
	v_add_f32_e32 v222, v222, v88
	v_add_f32_e32 v223, v223, v89
	v_cvt_pk_bf16_f32 v85, v88, v89
	v_mfma_f32_32x32x16_bf16 v[98:113], v[196:199], v[150:153], v[98:113]
	v_exp_f32_e32 v74, v74
	v_exp_f32_e32 v75, v75
	v_add_f32_e32 v178, v178, v74
	v_add_f32_e32 v218, v218, v75
	v_cvt_pk_bf16_f32 v74, v74, v75
	v_mfma_f32_32x32x16_bf16 v[114:129], v[184:187], v[154:157], 0
	v_exp_f32_e32 v76, v76
	v_exp_f32_e32 v77, v77
	v_add_f32_e32 v219, v219, v76
	v_add_f32_e32 v220, v220, v77
	v_cvt_pk_bf16_f32 v75, v76, v77
	v_mfma_f32_32x32x16_bf16 v[114:129], v[188:191], v[138:141], v[114:129]
	v_exp_f32_e32 v78, v78
	v_exp_f32_e32 v79, v79
	v_add_f32_e32 v178, v178, v78
	v_add_f32_e32 v218, v218, v79
	v_cvt_pk_bf16_f32 v76, v78, v79
	v_mfma_f32_32x32x16_bf16 v[114:129], v[192:195], v[142:145], v[114:129]
	v_exp_f32_e32 v80, v80
	v_exp_f32_e32 v81, v81
	v_add_f32_e32 v219, v219, v80
	v_add_f32_e32 v220, v220, v81
	v_cvt_pk_bf16_f32 v77, v80, v81
	v_mfma_f32_32x32x16_bf16 v[114:129], v[196:199], v[158:161], v[114:129]
	v_exp_f32_e32 v90, v90
	v_exp_f32_e32 v91, v91
	v_add_f32_e32 v179, v179, v90
	v_add_f32_e32 v221, v221, v91
	v_cvt_pk_bf16_f32 v90, v90, v91
	s_waitcnt lgkmcnt(4)
	v_mfma_f32_32x32x16_bf16 v[50:65], v[200:203], v[66:69], v[50:65]
	ds_read_b128 v[184:187], v183 offset:18432
	ds_read_b128 v[188:191], v183 offset:18464
	ds_read_b128 v[192:195], v183 offset:18496
	ds_read_b128 v[196:199], v183 offset:18528
	v_exp_f32_e32 v92, v92
	v_exp_f32_e32 v93, v93
	v_add_f32_e32 v222, v222, v92
	v_add_f32_e32 v223, v223, v93
	v_cvt_pk_bf16_f32 v91, v92, v93
	v_mfma_f32_32x32x16_bf16 v[34:49], v[204:207], v[66:69], v[34:49]
	v_exp_f32_e32 v94, v94
	v_exp_f32_e32 v95, v95
	v_add_f32_e32 v179, v179, v94
	v_add_f32_e32 v221, v221, v95
	v_cvt_pk_bf16_f32 v92, v94, v95
	v_mfma_f32_32x32x16_bf16 v[18:33], v[200:203], v[82:85], v[18:33]
	v_exp_f32_e32 v96, v96
	v_exp_f32_e32 v97, v97
	v_add_f32_e32 v222, v222, v96
	v_add_f32_e32 v223, v223, v97
	v_cvt_pk_bf16_f32 v93, v96, v97
	v_mfma_f32_32x32x16_bf16 v[2:17], v[204:207], v[82:85], v[2:17]
	v_exp_f32_e32 v98, v98
	v_exp_f32_e32 v99, v99
	v_add_f32_e32 v178, v178, v98
	v_add_f32_e32 v218, v218, v99
	v_cvt_pk_bf16_f32 v98, v98, v99
	s_waitcnt lgkmcnt(4)
	v_mfma_f32_32x32x16_bf16 v[50:65], v[208:211], v[74:77], v[50:65]
	ds_read_b64_tr_b16 v[200:201], v216 offset:13824
	ds_read_b64_tr_b16 v[202:203], v216 offset:14400
	ds_read_b64_tr_b16 v[204:205], v216 offset:13888
	ds_read_b64_tr_b16 v[206:207], v216 offset:14464
	v_exp_f32_e32 v100, v100
	v_exp_f32_e32 v101, v101
	v_add_f32_e32 v219, v219, v100
	v_add_f32_e32 v220, v220, v101
	v_cvt_pk_bf16_f32 v99, v100, v101
	v_mfma_f32_32x32x16_bf16 v[34:49], v[212:215], v[74:77], v[34:49]
	v_exp_f32_e32 v102, v102
	v_exp_f32_e32 v103, v103
	v_add_f32_e32 v178, v178, v102
	v_add_f32_e32 v218, v218, v103
	v_cvt_pk_bf16_f32 v100, v102, v103
	v_mfma_f32_32x32x16_bf16 v[18:33], v[208:211], v[90:93], v[18:33]
	v_exp_f32_e32 v104, v104
	v_exp_f32_e32 v105, v105
	v_add_f32_e32 v219, v219, v104
	v_add_f32_e32 v220, v220, v105
	v_cvt_pk_bf16_f32 v101, v104, v105
	v_mfma_f32_32x32x16_bf16 v[2:17], v[212:215], v[90:93], v[2:17]
	v_exp_f32_e32 v114, v114
	v_exp_f32_e32 v115, v115
	v_add_f32_e32 v179, v179, v114
	v_add_f32_e32 v221, v221, v115
	v_cvt_pk_bf16_f32 v114, v114, v115
	s_waitcnt lgkmcnt(4)
	v_mfma_f32_32x32x16_bf16 v[66:81], v[184:187], v[130:133], 0
	ds_read_b64_tr_b16 v[208:209], v216 offset:16128
	ds_read_b64_tr_b16 v[210:211], v216 offset:16704
	ds_read_b64_tr_b16 v[212:213], v216 offset:16192
	ds_read_b64_tr_b16 v[214:215], v216 offset:16768
	v_exp_f32_e32 v116, v116
	v_exp_f32_e32 v117, v117
	v_add_f32_e32 v222, v222, v116
	v_add_f32_e32 v223, v223, v117
	v_cvt_pk_bf16_f32 v115, v116, v117
	v_mfma_f32_32x32x16_bf16 v[66:81], v[188:191], v[134:137], v[66:81]
	v_exp_f32_e32 v118, v118
	v_exp_f32_e32 v119, v119
	v_add_f32_e32 v179, v179, v118
	v_add_f32_e32 v221, v221, v119
	v_cvt_pk_bf16_f32 v116, v118, v119
	v_mfma_f32_32x32x16_bf16 v[66:81], v[192:195], v[146:149], v[66:81]
	v_exp_f32_e32 v120, v120
	v_exp_f32_e32 v121, v121
	v_add_f32_e32 v222, v222, v120
	v_add_f32_e32 v223, v223, v121
	v_cvt_pk_bf16_f32 v117, v120, v121
	v_mfma_f32_32x32x16_bf16 v[66:81], v[196:199], v[150:153], v[66:81]
	v_exp_f32_e32 v106, v106
	v_exp_f32_e32 v107, v107
	v_add_f32_e32 v178, v178, v106
	v_add_f32_e32 v218, v218, v107
	v_cvt_pk_bf16_f32 v106, v106, v107
	s_waitcnt lgkmcnt(4)
	v_mfma_f32_32x32x16_bf16 v[50:65], v[200:203], v[98:101], v[50:65]
	v_exp_f32_e32 v108, v108
	v_exp_f32_e32 v109, v109
	v_add_f32_e32 v219, v219, v108
	v_add_f32_e32 v220, v220, v109
	v_cvt_pk_bf16_f32 v107, v108, v109
	v_mfma_f32_32x32x16_bf16 v[34:49], v[204:207], v[98:101], v[34:49]
	v_exp_f32_e32 v110, v110
	v_exp_f32_e32 v111, v111
	v_add_f32_e32 v178, v178, v110
	v_add_f32_e32 v218, v218, v111
	v_cvt_pk_bf16_f32 v108, v110, v111
	v_mfma_f32_32x32x16_bf16 v[18:33], v[200:203], v[114:117], v[18:33]
	s_waitcnt vmcnt(0)
	ds_write_b128 v180, v[162:165] offset:36864
	ds_write_b128 v180, v[166:169] offset:46080
	v_exp_f32_e32 v112, v112
	v_exp_f32_e32 v113, v113
	v_add_f32_e32 v219, v219, v112
	v_add_f32_e32 v220, v220, v113
	v_cvt_pk_bf16_f32 v109, v112, v113
	v_mfma_f32_32x32x16_bf16 v[2:17], v[204:207], v[114:117], v[2:17]
	v_exp_f32_e32 v122, v122
	v_exp_f32_e32 v123, v123
	v_add_f32_e32 v179, v179, v122
	v_add_f32_e32 v221, v221, v123
	v_cvt_pk_bf16_f32 v122, v122, v123
	v_mfma_f32_32x32x16_bf16 v[82:97], v[184:187], v[154:157], 0
	v_exp_f32_e32 v124, v124
	v_exp_f32_e32 v125, v125
	v_add_f32_e32 v222, v222, v124
	v_add_f32_e32 v223, v223, v125
	v_cvt_pk_bf16_f32 v123, v124, v125
	v_mfma_f32_32x32x16_bf16 v[82:97], v[188:191], v[138:141], v[82:97]
	v_exp_f32_e32 v126, v126
	v_exp_f32_e32 v127, v127
	v_add_f32_e32 v179, v179, v126
	v_add_f32_e32 v221, v221, v127
	v_cvt_pk_bf16_f32 v124, v126, v127
	v_mfma_f32_32x32x16_bf16 v[82:97], v[192:195], v[142:145], v[82:97]
	v_exp_f32_e32 v128, v128
	v_exp_f32_e32 v129, v129
	v_add_f32_e32 v222, v222, v128
	v_add_f32_e32 v223, v223, v129
	v_cvt_pk_bf16_f32 v125, v128, v129
	v_mfma_f32_32x32x16_bf16 v[82:97], v[196:199], v[158:161], v[82:97]
	s_waitcnt lgkmcnt(0)
	s_barrier
	global_load_dwordx4 v[162:165], v[176:177], off
	global_load_dwordx4 v[166:169], v[176:177], off offset:256
	ds_read_b128 v[184:187], v183 offset:23040
	ds_read_b128 v[188:191], v183 offset:23072
	ds_read_b128 v[192:195], v183 offset:23104
	ds_read_b128 v[196:199], v183 offset:23136
	v_exp_f32_e32 v66, v66
	v_exp_f32_e32 v67, v67
	v_add_f32_e32 v178, v178, v66
	v_add_f32_e32 v218, v218, v67
	v_cvt_pk_bf16_f32 v66, v66, v67
	v_mfma_f32_32x32x16_bf16 v[50:65], v[208:211], v[106:109], v[50:65]
	v_exp_f32_e32 v68, v68
	v_exp_f32_e32 v69, v69
	v_add_f32_e32 v219, v219, v68
	v_add_f32_e32 v220, v220, v69
	v_cvt_pk_bf16_f32 v67, v68, v69
	v_mfma_f32_32x32x16_bf16 v[34:49], v[212:215], v[106:109], v[34:49]
	v_lshl_add_u64 v[176:177], v[176:177], 0, s[8:9]
	v_exp_f32_e32 v70, v70
	v_exp_f32_e32 v71, v71
	v_add_f32_e32 v178, v178, v70
	v_add_f32_e32 v218, v218, v71
	v_cvt_pk_bf16_f32 v68, v70, v71
	v_mfma_f32_32x32x16_bf16 v[18:33], v[208:211], v[122:125], v[18:33]
	v_exp_f32_e32 v72, v72
	v_exp_f32_e32 v73, v73
	v_add_f32_e32 v219, v219, v72
	v_add_f32_e32 v220, v220, v73
	v_cvt_pk_bf16_f32 v69, v72, v73
	v_mfma_f32_32x32x16_bf16 v[2:17], v[212:215], v[122:125], v[2:17]
	v_exp_f32_e32 v82, v82
	v_exp_f32_e32 v83, v83
	v_add_f32_e32 v179, v179, v82
	v_add_f32_e32 v221, v221, v83
	v_cvt_pk_bf16_f32 v82, v82, v83
	s_waitcnt lgkmcnt(0)
	v_mfma_f32_32x32x16_bf16 v[98:113], v[184:187], v[130:133], 0
	ds_read_b64_tr_b16 v[200:201], v216 offset:27648
	ds_read_b64_tr_b16 v[202:203], v216 offset:28224
	ds_read_b64_tr_b16 v[204:205], v216 offset:27712
	ds_read_b64_tr_b16 v[206:207], v216 offset:28288
	v_exp_f32_e32 v84, v84
	v_exp_f32_e32 v85, v85
	v_add_f32_e32 v222, v222, v84
	v_add_f32_e32 v223, v223, v85
	v_cvt_pk_bf16_f32 v83, v84, v85
	v_mfma_f32_32x32x16_bf16 v[98:113], v[188:191], v[134:137], v[98:113]
	ds_read_b64_tr_b16 v[208:209], v216 offset:29952
	ds_read_b64_tr_b16 v[210:211], v216 offset:30528
	ds_read_b64_tr_b16 v[212:213], v216 offset:30016
	ds_read_b64_tr_b16 v[214:215], v216 offset:30592
	v_exp_f32_e32 v86, v86
	v_exp_f32_e32 v87, v87
	v_add_f32_e32 v179, v179, v86
	v_add_f32_e32 v221, v221, v87
	v_cvt_pk_bf16_f32 v84, v86, v87
	v_mfma_f32_32x32x16_bf16 v[98:113], v[192:195], v[146:149], v[98:113]
	v_exp_f32_e32 v88, v88
	v_exp_f32_e32 v89, v89
	v_add_f32_e32 v222, v222, v88
	v_add_f32_e32 v223, v223, v89
	v_cvt_pk_bf16_f32 v85, v88, v89
	v_mfma_f32_32x32x16_bf16 v[98:113], v[196:199], v[150:153], v[98:113]
	v_exp_f32_e32 v74, v74
	v_exp_f32_e32 v75, v75
	v_add_f32_e32 v178, v178, v74
	v_add_f32_e32 v218, v218, v75
	v_cvt_pk_bf16_f32 v74, v74, v75
	v_mfma_f32_32x32x16_bf16 v[114:129], v[184:187], v[154:157], 0
	v_exp_f32_e32 v76, v76
	v_exp_f32_e32 v77, v77
	v_add_f32_e32 v219, v219, v76
	v_add_f32_e32 v220, v220, v77
	v_cvt_pk_bf16_f32 v75, v76, v77
	v_mfma_f32_32x32x16_bf16 v[114:129], v[188:191], v[138:141], v[114:129]
	v_exp_f32_e32 v78, v78
	v_exp_f32_e32 v79, v79
	v_add_f32_e32 v178, v178, v78
	v_add_f32_e32 v218, v218, v79
	v_cvt_pk_bf16_f32 v76, v78, v79
	v_mfma_f32_32x32x16_bf16 v[114:129], v[192:195], v[142:145], v[114:129]
	v_exp_f32_e32 v80, v80
	v_exp_f32_e32 v81, v81
	v_add_f32_e32 v219, v219, v80
	v_add_f32_e32 v220, v220, v81
	v_cvt_pk_bf16_f32 v77, v80, v81
	v_mfma_f32_32x32x16_bf16 v[114:129], v[196:199], v[158:161], v[114:129]
	v_exp_f32_e32 v90, v90
	v_exp_f32_e32 v91, v91
	v_add_f32_e32 v179, v179, v90
	v_add_f32_e32 v221, v221, v91
	v_cvt_pk_bf16_f32 v90, v90, v91
	s_waitcnt lgkmcnt(4)
	v_mfma_f32_32x32x16_bf16 v[50:65], v[200:203], v[66:69], v[50:65]
	ds_read_b128 v[184:187], v183 offset:36864
	ds_read_b128 v[188:191], v183 offset:36896
	ds_read_b128 v[192:195], v183 offset:36928
	ds_read_b128 v[196:199], v183 offset:36960
	v_exp_f32_e32 v92, v92
	v_exp_f32_e32 v93, v93
	v_add_f32_e32 v222, v222, v92
	v_add_f32_e32 v223, v223, v93
	v_cvt_pk_bf16_f32 v91, v92, v93
	v_mfma_f32_32x32x16_bf16 v[34:49], v[204:207], v[66:69], v[34:49]
	v_exp_f32_e32 v94, v94
	v_exp_f32_e32 v95, v95
	v_add_f32_e32 v179, v179, v94
	v_add_f32_e32 v221, v221, v95
	v_cvt_pk_bf16_f32 v92, v94, v95
	v_mfma_f32_32x32x16_bf16 v[18:33], v[200:203], v[82:85], v[18:33]
	v_exp_f32_e32 v96, v96
	v_exp_f32_e32 v97, v97
	v_add_f32_e32 v222, v222, v96
	v_add_f32_e32 v223, v223, v97
	v_cvt_pk_bf16_f32 v93, v96, v97
	v_mfma_f32_32x32x16_bf16 v[2:17], v[204:207], v[82:85], v[2:17]
	v_exp_f32_e32 v98, v98
	v_exp_f32_e32 v99, v99
	v_add_f32_e32 v178, v178, v98
	v_add_f32_e32 v218, v218, v99
	v_cvt_pk_bf16_f32 v98, v98, v99
	s_waitcnt lgkmcnt(4)
	v_mfma_f32_32x32x16_bf16 v[50:65], v[208:211], v[74:77], v[50:65]
	ds_read_b64_tr_b16 v[200:201], v216 offset:32256
	ds_read_b64_tr_b16 v[202:203], v216 offset:32832
	ds_read_b64_tr_b16 v[204:205], v216 offset:32320
	ds_read_b64_tr_b16 v[206:207], v216 offset:32896
	v_exp_f32_e32 v100, v100
	v_exp_f32_e32 v101, v101
	v_add_f32_e32 v219, v219, v100
	v_add_f32_e32 v220, v220, v101
	v_cvt_pk_bf16_f32 v99, v100, v101
	v_mfma_f32_32x32x16_bf16 v[34:49], v[212:215], v[74:77], v[34:49]
	v_exp_f32_e32 v102, v102
	v_exp_f32_e32 v103, v103
	v_add_f32_e32 v178, v178, v102
	v_add_f32_e32 v218, v218, v103
	v_cvt_pk_bf16_f32 v100, v102, v103
	v_mfma_f32_32x32x16_bf16 v[18:33], v[208:211], v[90:93], v[18:33]
	v_exp_f32_e32 v104, v104
	v_exp_f32_e32 v105, v105
	v_add_f32_e32 v219, v219, v104
	v_add_f32_e32 v220, v220, v105
	v_cvt_pk_bf16_f32 v101, v104, v105
	v_mfma_f32_32x32x16_bf16 v[2:17], v[212:215], v[90:93], v[2:17]
	v_exp_f32_e32 v114, v114
	v_exp_f32_e32 v115, v115
	v_add_f32_e32 v179, v179, v114
	v_add_f32_e32 v221, v221, v115
	v_cvt_pk_bf16_f32 v114, v114, v115
	s_waitcnt lgkmcnt(4)
	v_mfma_f32_32x32x16_bf16 v[66:81], v[184:187], v[130:133], 0
	ds_read_b64_tr_b16 v[208:209], v216 offset:34560
	ds_read_b64_tr_b16 v[210:211], v216 offset:35136
	ds_read_b64_tr_b16 v[212:213], v216 offset:34624
	ds_read_b64_tr_b16 v[214:215], v216 offset:35200
	v_exp_f32_e32 v116, v116
	v_exp_f32_e32 v117, v117
	v_add_f32_e32 v222, v222, v116
	v_add_f32_e32 v223, v223, v117
	v_cvt_pk_bf16_f32 v115, v116, v117
	v_mfma_f32_32x32x16_bf16 v[66:81], v[188:191], v[134:137], v[66:81]
	v_exp_f32_e32 v118, v118
	v_exp_f32_e32 v119, v119
	v_add_f32_e32 v179, v179, v118
	v_add_f32_e32 v221, v221, v119
	v_cvt_pk_bf16_f32 v116, v118, v119
	v_mfma_f32_32x32x16_bf16 v[66:81], v[192:195], v[146:149], v[66:81]
	v_exp_f32_e32 v120, v120
	v_exp_f32_e32 v121, v121
	v_add_f32_e32 v222, v222, v120
	v_add_f32_e32 v223, v223, v121
	v_cvt_pk_bf16_f32 v117, v120, v121
	v_mfma_f32_32x32x16_bf16 v[66:81], v[196:199], v[150:153], v[66:81]
	v_exp_f32_e32 v106, v106
	v_exp_f32_e32 v107, v107
	v_add_f32_e32 v178, v178, v106
	v_add_f32_e32 v218, v218, v107
	v_cvt_pk_bf16_f32 v106, v106, v107
	s_waitcnt lgkmcnt(4)
	v_mfma_f32_32x32x16_bf16 v[50:65], v[200:203], v[98:101], v[50:65]
	v_exp_f32_e32 v108, v108
	v_exp_f32_e32 v109, v109
	v_add_f32_e32 v219, v219, v108
	v_add_f32_e32 v220, v220, v109
	v_cvt_pk_bf16_f32 v107, v108, v109
	v_mfma_f32_32x32x16_bf16 v[34:49], v[204:207], v[98:101], v[34:49]
	v_exp_f32_e32 v110, v110
	v_exp_f32_e32 v111, v111
	v_add_f32_e32 v178, v178, v110
	v_add_f32_e32 v218, v218, v111
	v_cvt_pk_bf16_f32 v108, v110, v111
	v_mfma_f32_32x32x16_bf16 v[18:33], v[200:203], v[114:117], v[18:33]
	s_waitcnt vmcnt(0)
	ds_write_b128 v180, v[162:165]
	ds_write_b128 v180, v[166:169] offset:9216
	v_exp_f32_e32 v112, v112
	v_exp_f32_e32 v113, v113
	v_add_f32_e32 v219, v219, v112
	v_add_f32_e32 v220, v220, v113
	v_cvt_pk_bf16_f32 v109, v112, v113
	v_mfma_f32_32x32x16_bf16 v[2:17], v[204:207], v[114:117], v[2:17]
	v_exp_f32_e32 v122, v122
	v_exp_f32_e32 v123, v123
	v_add_f32_e32 v179, v179, v122
	v_add_f32_e32 v221, v221, v123
	v_cvt_pk_bf16_f32 v122, v122, v123
	v_mfma_f32_32x32x16_bf16 v[82:97], v[184:187], v[154:157], 0
	v_exp_f32_e32 v124, v124
	v_exp_f32_e32 v125, v125
	v_add_f32_e32 v222, v222, v124
	v_add_f32_e32 v223, v223, v125
	v_cvt_pk_bf16_f32 v123, v124, v125
	v_mfma_f32_32x32x16_bf16 v[82:97], v[188:191], v[138:141], v[82:97]
	v_exp_f32_e32 v126, v126
	v_exp_f32_e32 v127, v127
	v_add_f32_e32 v179, v179, v126
	v_add_f32_e32 v221, v221, v127
	v_cvt_pk_bf16_f32 v124, v126, v127
	v_mfma_f32_32x32x16_bf16 v[82:97], v[192:195], v[142:145], v[82:97]
	v_exp_f32_e32 v128, v128
	v_exp_f32_e32 v129, v129
	v_add_f32_e32 v222, v222, v128
	v_add_f32_e32 v223, v223, v129
	v_cvt_pk_bf16_f32 v125, v128, v129
	v_mfma_f32_32x32x16_bf16 v[82:97], v[196:199], v[158:161], v[82:97]
	s_waitcnt lgkmcnt(0)
	s_barrier
	global_load_dwordx4 v[162:165], v[176:177], off
	global_load_dwordx4 v[166:169], v[176:177], off offset:256
	ds_read_b128 v[184:187], v183 offset:41472
	ds_read_b128 v[188:191], v183 offset:41504
	ds_read_b128 v[192:195], v183 offset:41536
	ds_read_b128 v[196:199], v183 offset:41568
	v_exp_f32_e32 v66, v66
	v_exp_f32_e32 v67, v67
	v_add_f32_e32 v178, v178, v66
	v_add_f32_e32 v218, v218, v67
	v_cvt_pk_bf16_f32 v66, v66, v67
	v_mfma_f32_32x32x16_bf16 v[50:65], v[208:211], v[106:109], v[50:65]
	v_exp_f32_e32 v68, v68
	v_exp_f32_e32 v69, v69
	v_add_f32_e32 v219, v219, v68
	v_add_f32_e32 v220, v220, v69
	v_cvt_pk_bf16_f32 v67, v68, v69
	v_mfma_f32_32x32x16_bf16 v[34:49], v[212:215], v[106:109], v[34:49]
	v_lshl_add_u64 v[176:177], v[176:177], 0, s[8:9]
	v_exp_f32_e32 v70, v70
	v_exp_f32_e32 v71, v71
	v_add_f32_e32 v178, v178, v70
	v_add_f32_e32 v218, v218, v71
	v_cvt_pk_bf16_f32 v68, v70, v71
	v_mfma_f32_32x32x16_bf16 v[18:33], v[208:211], v[122:125], v[18:33]
	v_exp_f32_e32 v72, v72
	v_exp_f32_e32 v73, v73
	v_add_f32_e32 v219, v219, v72
	v_add_f32_e32 v220, v220, v73
	v_cvt_pk_bf16_f32 v69, v72, v73
	v_mfma_f32_32x32x16_bf16 v[2:17], v[212:215], v[122:125], v[2:17]
	v_exp_f32_e32 v82, v82
	v_exp_f32_e32 v83, v83
	v_add_f32_e32 v179, v179, v82
	v_add_f32_e32 v221, v221, v83
	v_cvt_pk_bf16_f32 v82, v82, v83
	s_waitcnt lgkmcnt(0)
	v_mfma_f32_32x32x16_bf16 v[98:113], v[184:187], v[130:133], 0
	ds_read_b64_tr_b16 v[200:201], v216 offset:46080
	ds_read_b64_tr_b16 v[202:203], v216 offset:46656
	ds_read_b64_tr_b16 v[204:205], v216 offset:46144
	ds_read_b64_tr_b16 v[206:207], v216 offset:46720
	v_exp_f32_e32 v84, v84
	v_exp_f32_e32 v85, v85
	v_add_f32_e32 v222, v222, v84
	v_add_f32_e32 v223, v223, v85
	v_cvt_pk_bf16_f32 v83, v84, v85
	v_mfma_f32_32x32x16_bf16 v[98:113], v[188:191], v[134:137], v[98:113]
	ds_read_b64_tr_b16 v[208:209], v216 offset:48384
	ds_read_b64_tr_b16 v[210:211], v216 offset:48960
	ds_read_b64_tr_b16 v[212:213], v216 offset:48448
	ds_read_b64_tr_b16 v[214:215], v216 offset:49024
	v_exp_f32_e32 v86, v86
	v_exp_f32_e32 v87, v87
	v_add_f32_e32 v179, v179, v86
	v_add_f32_e32 v221, v221, v87
	v_cvt_pk_bf16_f32 v84, v86, v87
	v_mfma_f32_32x32x16_bf16 v[98:113], v[192:195], v[146:149], v[98:113]
	v_exp_f32_e32 v88, v88
	v_exp_f32_e32 v89, v89
	v_add_f32_e32 v222, v222, v88
	v_add_f32_e32 v223, v223, v89
	v_cvt_pk_bf16_f32 v85, v88, v89
	v_mfma_f32_32x32x16_bf16 v[98:113], v[196:199], v[150:153], v[98:113]
	v_exp_f32_e32 v74, v74
	v_exp_f32_e32 v75, v75
	v_add_f32_e32 v178, v178, v74
	v_add_f32_e32 v218, v218, v75
	v_cvt_pk_bf16_f32 v74, v74, v75
	v_mfma_f32_32x32x16_bf16 v[114:129], v[184:187], v[154:157], 0
	v_exp_f32_e32 v76, v76
	v_exp_f32_e32 v77, v77
	v_add_f32_e32 v219, v219, v76
	v_add_f32_e32 v220, v220, v77
	v_cvt_pk_bf16_f32 v75, v76, v77
	v_mfma_f32_32x32x16_bf16 v[114:129], v[188:191], v[138:141], v[114:129]
	v_exp_f32_e32 v78, v78
	v_exp_f32_e32 v79, v79
	v_add_f32_e32 v178, v178, v78
	v_add_f32_e32 v218, v218, v79
	v_cvt_pk_bf16_f32 v76, v78, v79
	v_mfma_f32_32x32x16_bf16 v[114:129], v[192:195], v[142:145], v[114:129]
	v_exp_f32_e32 v80, v80
	v_exp_f32_e32 v81, v81
	v_add_f32_e32 v219, v219, v80
	v_add_f32_e32 v220, v220, v81
	v_cvt_pk_bf16_f32 v77, v80, v81
	v_mfma_f32_32x32x16_bf16 v[114:129], v[196:199], v[158:161], v[114:129]
	v_exp_f32_e32 v90, v90
	v_exp_f32_e32 v91, v91
	v_add_f32_e32 v179, v179, v90
	v_add_f32_e32 v221, v221, v91
	v_cvt_pk_bf16_f32 v90, v90, v91
	s_waitcnt lgkmcnt(4)
	v_mfma_f32_32x32x16_bf16 v[50:65], v[200:203], v[66:69], v[50:65]
	ds_read_b128 v[184:187], v183
	ds_read_b128 v[188:191], v183 offset:32
	ds_read_b128 v[192:195], v183 offset:64
	ds_read_b128 v[196:199], v183 offset:96
	v_exp_f32_e32 v92, v92
	v_exp_f32_e32 v93, v93
	v_add_f32_e32 v222, v222, v92
	v_add_f32_e32 v223, v223, v93
	v_cvt_pk_bf16_f32 v91, v92, v93
	v_mfma_f32_32x32x16_bf16 v[34:49], v[204:207], v[66:69], v[34:49]
	v_exp_f32_e32 v94, v94
	v_exp_f32_e32 v95, v95
	v_add_f32_e32 v179, v179, v94
	v_add_f32_e32 v221, v221, v95
	v_cvt_pk_bf16_f32 v92, v94, v95
	v_mfma_f32_32x32x16_bf16 v[18:33], v[200:203], v[82:85], v[18:33]
	v_exp_f32_e32 v96, v96
	v_exp_f32_e32 v97, v97
	v_add_f32_e32 v222, v222, v96
	v_add_f32_e32 v223, v223, v97
	v_cvt_pk_bf16_f32 v93, v96, v97
	v_mfma_f32_32x32x16_bf16 v[2:17], v[204:207], v[82:85], v[2:17]
	v_exp_f32_e32 v98, v98
	v_exp_f32_e32 v99, v99
	v_add_f32_e32 v178, v178, v98
	v_add_f32_e32 v218, v218, v99
	v_cvt_pk_bf16_f32 v98, v98, v99
	s_waitcnt lgkmcnt(4)
	v_mfma_f32_32x32x16_bf16 v[50:65], v[208:211], v[74:77], v[50:65]
	ds_read_b64_tr_b16 v[200:201], v216 offset:50688
	ds_read_b64_tr_b16 v[202:203], v216 offset:51264
	ds_read_b64_tr_b16 v[204:205], v216 offset:50752
	ds_read_b64_tr_b16 v[206:207], v216 offset:51328
	v_exp_f32_e32 v100, v100
	v_exp_f32_e32 v101, v101
	v_add_f32_e32 v219, v219, v100
	v_add_f32_e32 v220, v220, v101
	v_cvt_pk_bf16_f32 v99, v100, v101
	v_mfma_f32_32x32x16_bf16 v[34:49], v[212:215], v[74:77], v[34:49]
	v_exp_f32_e32 v102, v102
	v_exp_f32_e32 v103, v103
	v_add_f32_e32 v178, v178, v102
	v_add_f32_e32 v218, v218, v103
	v_cvt_pk_bf16_f32 v100, v102, v103
	v_mfma_f32_32x32x16_bf16 v[18:33], v[208:211], v[90:93], v[18:33]
	v_exp_f32_e32 v104, v104
	v_exp_f32_e32 v105, v105
	v_add_f32_e32 v219, v219, v104
	v_add_f32_e32 v220, v220, v105
	v_cvt_pk_bf16_f32 v101, v104, v105
	v_mfma_f32_32x32x16_bf16 v[2:17], v[212:215], v[90:93], v[2:17]
	v_exp_f32_e32 v114, v114
	v_exp_f32_e32 v115, v115
	v_add_f32_e32 v179, v179, v114
	v_add_f32_e32 v221, v221, v115
	v_cvt_pk_bf16_f32 v114, v114, v115
	s_waitcnt lgkmcnt(4)
	v_mfma_f32_32x32x16_bf16 v[66:81], v[184:187], v[130:133], 0
	ds_read_b64_tr_b16 v[208:209], v216 offset:52992
	ds_read_b64_tr_b16 v[210:211], v216 offset:53568
	ds_read_b64_tr_b16 v[212:213], v216 offset:53056
	ds_read_b64_tr_b16 v[214:215], v216 offset:53632
	v_exp_f32_e32 v116, v116
	v_exp_f32_e32 v117, v117
	v_add_f32_e32 v222, v222, v116
	v_add_f32_e32 v223, v223, v117
	v_cvt_pk_bf16_f32 v115, v116, v117
	v_mfma_f32_32x32x16_bf16 v[66:81], v[188:191], v[134:137], v[66:81]
	v_exp_f32_e32 v118, v118
	v_exp_f32_e32 v119, v119
	v_add_f32_e32 v179, v179, v118
	v_add_f32_e32 v221, v221, v119
	v_cvt_pk_bf16_f32 v116, v118, v119
	v_mfma_f32_32x32x16_bf16 v[66:81], v[192:195], v[146:149], v[66:81]
	v_exp_f32_e32 v120, v120
	v_exp_f32_e32 v121, v121
	v_add_f32_e32 v222, v222, v120
	v_add_f32_e32 v223, v223, v121
	v_cvt_pk_bf16_f32 v117, v120, v121
	v_mfma_f32_32x32x16_bf16 v[66:81], v[196:199], v[150:153], v[66:81]
	v_exp_f32_e32 v106, v106
	v_exp_f32_e32 v107, v107
	v_add_f32_e32 v178, v178, v106
	v_add_f32_e32 v218, v218, v107
	v_cvt_pk_bf16_f32 v106, v106, v107
	s_waitcnt lgkmcnt(4)
	v_mfma_f32_32x32x16_bf16 v[50:65], v[200:203], v[98:101], v[50:65]
	v_exp_f32_e32 v108, v108
	v_exp_f32_e32 v109, v109
	v_add_f32_e32 v219, v219, v108
	v_add_f32_e32 v220, v220, v109
	v_cvt_pk_bf16_f32 v107, v108, v109
	v_mfma_f32_32x32x16_bf16 v[34:49], v[204:207], v[98:101], v[34:49]
	v_exp_f32_e32 v110, v110
	v_exp_f32_e32 v111, v111
	v_add_f32_e32 v178, v178, v110
	v_add_f32_e32 v218, v218, v111
	v_cvt_pk_bf16_f32 v108, v110, v111
	v_mfma_f32_32x32x16_bf16 v[18:33], v[200:203], v[114:117], v[18:33]
	s_waitcnt vmcnt(0)
	ds_write_b128 v180, v[162:165] offset:18432
	ds_write_b128 v180, v[166:169] offset:27648
	v_exp_f32_e32 v112, v112
	v_exp_f32_e32 v113, v113
	v_add_f32_e32 v219, v219, v112
	v_add_f32_e32 v220, v220, v113
	v_cvt_pk_bf16_f32 v109, v112, v113
	v_mfma_f32_32x32x16_bf16 v[2:17], v[204:207], v[114:117], v[2:17]
	v_exp_f32_e32 v122, v122
	v_exp_f32_e32 v123, v123
	v_add_f32_e32 v179, v179, v122
	v_add_f32_e32 v221, v221, v123
	v_cvt_pk_bf16_f32 v122, v122, v123
	v_mfma_f32_32x32x16_bf16 v[82:97], v[184:187], v[154:157], 0
	v_exp_f32_e32 v124, v124
	v_exp_f32_e32 v125, v125
	v_add_f32_e32 v222, v222, v124
	v_add_f32_e32 v223, v223, v125
	v_cvt_pk_bf16_f32 v123, v124, v125
	v_mfma_f32_32x32x16_bf16 v[82:97], v[188:191], v[138:141], v[82:97]
	v_exp_f32_e32 v126, v126
	v_exp_f32_e32 v127, v127
	v_add_f32_e32 v179, v179, v126
	v_add_f32_e32 v221, v221, v127
	v_cvt_pk_bf16_f32 v124, v126, v127
	v_mfma_f32_32x32x16_bf16 v[82:97], v[192:195], v[142:145], v[82:97]
	v_exp_f32_e32 v128, v128
	v_exp_f32_e32 v129, v129
	v_add_f32_e32 v222, v222, v128
	v_add_f32_e32 v223, v223, v129
	v_cvt_pk_bf16_f32 v125, v128, v129
	v_mfma_f32_32x32x16_bf16 v[82:97], v[196:199], v[158:161], v[82:97]
	s_add_i32 s30, s30, 1
	s_cmpk_lt_u32 s30, 84
	s_cbranch_scc1 .Lat_loop
	s_waitcnt lgkmcnt(0)
	s_barrier
	global_load_dwordx4 v[162:165], v[176:177], off
	global_load_dwordx4 v[166:169], v[176:177], off offset:256
	ds_read_b128 v[184:187], v183 offset:4608
	ds_read_b128 v[188:191], v183 offset:4640
	ds_read_b128 v[192:195], v183 offset:4672
	ds_read_b128 v[196:199], v183 offset:4704
	v_exp_f32_e32 v66, v66
	v_exp_f32_e32 v67, v67
	v_add_f32_e32 v178, v178, v66
	v_add_f32_e32 v218, v218, v67
	v_cvt_pk_bf16_f32 v66, v66, v67
	v_mfma_f32_32x32x16_bf16 v[50:65], v[208:211], v[106:109], v[50:65]
	v_exp_f32_e32 v68, v68
	v_exp_f32_e32 v69, v69
	v_add_f32_e32 v219, v219, v68
	v_add_f32_e32 v220, v220, v69
	v_cvt_pk_bf16_f32 v67, v68, v69
	v_mfma_f32_32x32x16_bf16 v[34:49], v[212:215], v[106:109], v[34:49]
	v_lshl_add_u64 v[176:177], v[176:177], 0, s[8:9]
	v_exp_f32_e32 v70, v70
	v_exp_f32_e32 v71, v71
	v_add_f32_e32 v178, v178, v70
	v_add_f32_e32 v218, v218, v71
	v_cvt_pk_bf16_f32 v68, v70, v71
	v_mfma_f32_32x32x16_bf16 v[18:33], v[208:211], v[122:125], v[18:33]
	v_exp_f32_e32 v72, v72
	v_exp_f32_e32 v73, v73
	v_add_f32_e32 v219, v219, v72
	v_add_f32_e32 v220, v220, v73
	v_cvt_pk_bf16_f32 v69, v72, v73
	v_mfma_f32_32x32x16_bf16 v[2:17], v[212:215], v[122:125], v[2:17]
	v_exp_f32_e32 v82, v82
	v_exp_f32_e32 v83, v83
	v_add_f32_e32 v179, v179, v82
	v_add_f32_e32 v221, v221, v83
	v_cvt_pk_bf16_f32 v82, v82, v83
	s_waitcnt lgkmcnt(0)
	v_mfma_f32_32x32x16_bf16 v[98:113], v[184:187], v[130:133], 0
	ds_read_b64_tr_b16 v[200:201], v216 offset:9216
	ds_read_b64_tr_b16 v[202:203], v216 offset:9792
	ds_read_b64_tr_b16 v[204:205], v216 offset:9280
	ds_read_b64_tr_b16 v[206:207], v216 offset:9856
	v_exp_f32_e32 v84, v84
	v_exp_f32_e32 v85, v85
	v_add_f32_e32 v222, v222, v84
	v_add_f32_e32 v223, v223, v85
	v_cvt_pk_bf16_f32 v83, v84, v85
	v_mfma_f32_32x32x16_bf16 v[98:113], v[188:191], v[134:137], v[98:113]
	ds_read_b64_tr_b16 v[208:209], v216 offset:11520
	ds_read_b64_tr_b16 v[210:211], v216 offset:12096
	ds_read_b64_tr_b16 v[212:213], v216 offset:11584
	ds_read_b64_tr_b16 v[214:215], v216 offset:12160
	v_exp_f32_e32 v86, v86
	v_exp_f32_e32 v87, v87
	v_add_f32_e32 v179, v179, v86
	v_add_f32_e32 v221, v221, v87
	v_cvt_pk_bf16_f32 v84, v86, v87
	v_mfma_f32_32x32x16_bf16 v[98:113], v[192:195], v[146:149], v[98:113]
	v_exp_f32_e32 v88, v88
	v_exp_f32_e32 v89, v89
	v_add_f32_e32 v222, v222, v88
	v_add_f32_e32 v223, v223, v89
	v_cvt_pk_bf16_f32 v85, v88, v89
	v_mfma_f32_32x32x16_bf16 v[98:113], v[196:199], v[150:153], v[98:113]
	v_exp_f32_e32 v74, v74
	v_exp_f32_e32 v75, v75
	v_add_f32_e32 v178, v178, v74
	v_add_f32_e32 v218, v218, v75
	v_cvt_pk_bf16_f32 v74, v74, v75
	v_mfma_f32_32x32x16_bf16 v[114:129], v[184:187], v[154:157], 0
	v_exp_f32_e32 v76, v76
	v_exp_f32_e32 v77, v77
	v_add_f32_e32 v219, v219, v76
	v_add_f32_e32 v220, v220, v77
	v_cvt_pk_bf16_f32 v75, v76, v77
	v_mfma_f32_32x32x16_bf16 v[114:129], v[188:191], v[138:141], v[114:129]
	v_exp_f32_e32 v78, v78
	v_exp_f32_e32 v79, v79
	v_add_f32_e32 v178, v178, v78
	v_add_f32_e32 v218, v218, v79
	v_cvt_pk_bf16_f32 v76, v78, v79
	v_mfma_f32_32x32x16_bf16 v[114:129], v[192:195], v[142:145], v[114:129]
	v_exp_f32_e32 v80, v80
	v_exp_f32_e32 v81, v81
	v_add_f32_e32 v219, v219, v80
	v_add_f32_e32 v220, v220, v81
	v_cvt_pk_bf16_f32 v77, v80, v81
	v_mfma_f32_32x32x16_bf16 v[114:129], v[196:199], v[158:161], v[114:129]
	v_exp_f32_e32 v90, v90
	v_exp_f32_e32 v91, v91
	v_add_f32_e32 v179, v179, v90
	v_add_f32_e32 v221, v221, v91
	v_cvt_pk_bf16_f32 v90, v90, v91
	s_waitcnt lgkmcnt(4)
	v_mfma_f32_32x32x16_bf16 v[50:65], v[200:203], v[66:69], v[50:65]
	ds_read_b128 v[184:187], v183 offset:18432
	ds_read_b128 v[188:191], v183 offset:18464
	ds_read_b128 v[192:195], v183 offset:18496
	ds_read_b128 v[196:199], v183 offset:18528
	v_exp_f32_e32 v92, v92
	v_exp_f32_e32 v93, v93
	v_add_f32_e32 v222, v222, v92
	v_add_f32_e32 v223, v223, v93
	v_cvt_pk_bf16_f32 v91, v92, v93
	v_mfma_f32_32x32x16_bf16 v[34:49], v[204:207], v[66:69], v[34:49]
	v_exp_f32_e32 v94, v94
	v_exp_f32_e32 v95, v95
	v_add_f32_e32 v179, v179, v94
	v_add_f32_e32 v221, v221, v95
	v_cvt_pk_bf16_f32 v92, v94, v95
	v_mfma_f32_32x32x16_bf16 v[18:33], v[200:203], v[82:85], v[18:33]
	v_exp_f32_e32 v96, v96
	v_exp_f32_e32 v97, v97
	v_add_f32_e32 v222, v222, v96
	v_add_f32_e32 v223, v223, v97
	v_cvt_pk_bf16_f32 v93, v96, v97
	v_mfma_f32_32x32x16_bf16 v[2:17], v[204:207], v[82:85], v[2:17]
	v_exp_f32_e32 v98, v98
	v_exp_f32_e32 v99, v99
	v_add_f32_e32 v178, v178, v98
	v_add_f32_e32 v218, v218, v99
	v_cvt_pk_bf16_f32 v98, v98, v99
	s_waitcnt lgkmcnt(4)
	v_mfma_f32_32x32x16_bf16 v[50:65], v[208:211], v[74:77], v[50:65]
	ds_read_b64_tr_b16 v[200:201], v216 offset:13824
	ds_read_b64_tr_b16 v[202:203], v216 offset:14400
	ds_read_b64_tr_b16 v[204:205], v216 offset:13888
	ds_read_b64_tr_b16 v[206:207], v216 offset:14464
	v_exp_f32_e32 v100, v100
	v_exp_f32_e32 v101, v101
	v_add_f32_e32 v219, v219, v100
	v_add_f32_e32 v220, v220, v101
	v_cvt_pk_bf16_f32 v99, v100, v101
	v_mfma_f32_32x32x16_bf16 v[34:49], v[212:215], v[74:77], v[34:49]
	v_exp_f32_e32 v102, v102
	v_exp_f32_e32 v103, v103
	v_add_f32_e32 v178, v178, v102
	v_add_f32_e32 v218, v218, v103
	v_cvt_pk_bf16_f32 v100, v102, v103
	v_mfma_f32_32x32x16_bf16 v[18:33], v[208:211], v[90:93], v[18:33]
	v_exp_f32_e32 v104, v104
	v_exp_f32_e32 v105, v105
	v_add_f32_e32 v219, v219, v104
	v_add_f32_e32 v220, v220, v105
	v_cvt_pk_bf16_f32 v101, v104, v105
	v_mfma_f32_32x32x16_bf16 v[2:17], v[212:215], v[90:93], v[2:17]
	v_exp_f32_e32 v114, v114
	v_exp_f32_e32 v115, v115
	v_add_f32_e32 v179, v179, v114
	v_add_f32_e32 v221, v221, v115
	v_cvt_pk_bf16_f32 v114, v114, v115
	s_waitcnt lgkmcnt(4)
	v_mfma_f32_32x32x16_bf16 v[66:81], v[184:187], v[130:133], 0
	ds_read_b64_tr_b16 v[208:209], v216 offset:16128
	ds_read_b64_tr_b16 v[210:211], v216 offset:16704
	ds_read_b64_tr_b16 v[212:213], v216 offset:16192
	ds_read_b64_tr_b16 v[214:215], v216 offset:16768
	v_exp_f32_e32 v116, v116
	v_exp_f32_e32 v117, v117
	v_add_f32_e32 v222, v222, v116
	v_add_f32_e32 v223, v223, v117
	v_cvt_pk_bf16_f32 v115, v116, v117
	v_mfma_f32_32x32x16_bf16 v[66:81], v[188:191], v[134:137], v[66:81]
	v_exp_f32_e32 v118, v118
	v_exp_f32_e32 v119, v119
	v_add_f32_e32 v179, v179, v118
	v_add_f32_e32 v221, v221, v119
	v_cvt_pk_bf16_f32 v116, v118, v119
	v_mfma_f32_32x32x16_bf16 v[66:81], v[192:195], v[146:149], v[66:81]
	v_exp_f32_e32 v120, v120
	v_exp_f32_e32 v121, v121
	v_add_f32_e32 v222, v222, v120
	v_add_f32_e32 v223, v223, v121
	v_cvt_pk_bf16_f32 v117, v120, v121
	v_mfma_f32_32x32x16_bf16 v[66:81], v[196:199], v[150:153], v[66:81]
	v_exp_f32_e32 v106, v106
	v_exp_f32_e32 v107, v107
	v_add_f32_e32 v178, v178, v106
	v_add_f32_e32 v218, v218, v107
	v_cvt_pk_bf16_f32 v106, v106, v107
	s_waitcnt lgkmcnt(4)
	v_mfma_f32_32x32x16_bf16 v[50:65], v[200:203], v[98:101], v[50:65]
	v_exp_f32_e32 v108, v108
	v_exp_f32_e32 v109, v109
	v_add_f32_e32 v219, v219, v108
	v_add_f32_e32 v220, v220, v109
	v_cvt_pk_bf16_f32 v107, v108, v109
	v_mfma_f32_32x32x16_bf16 v[34:49], v[204:207], v[98:101], v[34:49]
	v_exp_f32_e32 v110, v110
	v_exp_f32_e32 v111, v111
	v_add_f32_e32 v178, v178, v110
	v_add_f32_e32 v218, v218, v111
	v_cvt_pk_bf16_f32 v108, v110, v111
	v_mfma_f32_32x32x16_bf16 v[18:33], v[200:203], v[114:117], v[18:33]
	s_waitcnt vmcnt(0)
	ds_write_b128 v180, v[162:165] offset:36864
	ds_write_b128 v180, v[166:169] offset:46080
	v_exp_f32_e32 v112, v112
	v_exp_f32_e32 v113, v113
	v_add_f32_e32 v219, v219, v112
	v_add_f32_e32 v220, v220, v113
	v_cvt_pk_bf16_f32 v109, v112, v113
	v_mfma_f32_32x32x16_bf16 v[2:17], v[204:207], v[114:117], v[2:17]
	v_exp_f32_e32 v122, v122
	v_exp_f32_e32 v123, v123
	v_add_f32_e32 v179, v179, v122
	v_add_f32_e32 v221, v221, v123
	v_cvt_pk_bf16_f32 v122, v122, v123
	v_mfma_f32_32x32x16_bf16 v[82:97], v[184:187], v[154:157], 0
	v_exp_f32_e32 v124, v124
	v_exp_f32_e32 v125, v125
	v_add_f32_e32 v222, v222, v124
	v_add_f32_e32 v223, v223, v125
	v_cvt_pk_bf16_f32 v123, v124, v125
	v_mfma_f32_32x32x16_bf16 v[82:97], v[188:191], v[138:141], v[82:97]
	v_exp_f32_e32 v126, v126
	v_exp_f32_e32 v127, v127
	v_add_f32_e32 v179, v179, v126
	v_add_f32_e32 v221, v221, v127
	v_cvt_pk_bf16_f32 v124, v126, v127
	v_mfma_f32_32x32x16_bf16 v[82:97], v[192:195], v[142:145], v[82:97]
	v_exp_f32_e32 v128, v128
	v_exp_f32_e32 v129, v129
	v_add_f32_e32 v222, v222, v128
	v_add_f32_e32 v223, v223, v129
	v_cvt_pk_bf16_f32 v125, v128, v129
	v_mfma_f32_32x32x16_bf16 v[82:97], v[196:199], v[158:161], v[82:97]
	s_waitcnt lgkmcnt(0)
	s_barrier
	global_load_dwordx4 v[162:165], v[176:177], off
	global_load_dwordx4 v[166:169], v[176:177], off offset:256
	ds_read_b128 v[184:187], v183 offset:23040
	ds_read_b128 v[188:191], v183 offset:23072
	ds_read_b128 v[192:195], v183 offset:23104
	ds_read_b128 v[196:199], v183 offset:23136
	v_exp_f32_e32 v66, v66
	v_exp_f32_e32 v67, v67
	v_add_f32_e32 v178, v178, v66
	v_add_f32_e32 v218, v218, v67
	v_cvt_pk_bf16_f32 v66, v66, v67
	v_mfma_f32_32x32x16_bf16 v[50:65], v[208:211], v[106:109], v[50:65]
	v_exp_f32_e32 v68, v68
	v_exp_f32_e32 v69, v69
	v_add_f32_e32 v219, v219, v68
	v_add_f32_e32 v220, v220, v69
	v_cvt_pk_bf16_f32 v67, v68, v69
	v_mfma_f32_32x32x16_bf16 v[34:49], v[212:215], v[106:109], v[34:49]
	v_lshl_add_u64 v[176:177], v[176:177], 0, s[8:9]
	v_exp_f32_e32 v70, v70
	v_exp_f32_e32 v71, v71
	v_add_f32_e32 v178, v178, v70
	v_add_f32_e32 v218, v218, v71
	v_cvt_pk_bf16_f32 v68, v70, v71
	v_mfma_f32_32x32x16_bf16 v[18:33], v[208:211], v[122:125], v[18:33]
	v_exp_f32_e32 v72, v72
	v_exp_f32_e32 v73, v73
	v_add_f32_e32 v219, v219, v72
	v_add_f32_e32 v220, v220, v73
	v_cvt_pk_bf16_f32 v69, v72, v73
	v_mfma_f32_32x32x16_bf16 v[2:17], v[212:215], v[122:125], v[2:17]
	v_exp_f32_e32 v82, v82
	v_exp_f32_e32 v83, v83
	v_add_f32_e32 v179, v179, v82
	v_add_f32_e32 v221, v221, v83
	v_cvt_pk_bf16_f32 v82, v82, v83
	s_waitcnt lgkmcnt(0)
	v_mfma_f32_32x32x16_bf16 v[98:113], v[184:187], v[130:133], 0
	ds_read_b64_tr_b16 v[200:201], v216 offset:27648
	ds_read_b64_tr_b16 v[202:203], v216 offset:28224
	ds_read_b64_tr_b16 v[204:205], v216 offset:27712
	ds_read_b64_tr_b16 v[206:207], v216 offset:28288
	v_exp_f32_e32 v84, v84
	v_exp_f32_e32 v85, v85
	v_add_f32_e32 v222, v222, v84
	v_add_f32_e32 v223, v223, v85
	v_cvt_pk_bf16_f32 v83, v84, v85
	v_mfma_f32_32x32x16_bf16 v[98:113], v[188:191], v[134:137], v[98:113]
	ds_read_b64_tr_b16 v[208:209], v216 offset:29952
	ds_read_b64_tr_b16 v[210:211], v216 offset:30528
	ds_read_b64_tr_b16 v[212:213], v216 offset:30016
	ds_read_b64_tr_b16 v[214:215], v216 offset:30592
	v_exp_f32_e32 v86, v86
	v_exp_f32_e32 v87, v87
	v_add_f32_e32 v179, v179, v86
	v_add_f32_e32 v221, v221, v87
	v_cvt_pk_bf16_f32 v84, v86, v87
	v_mfma_f32_32x32x16_bf16 v[98:113], v[192:195], v[146:149], v[98:113]
	v_exp_f32_e32 v88, v88
	v_exp_f32_e32 v89, v89
	v_add_f32_e32 v222, v222, v88
	v_add_f32_e32 v223, v223, v89
	v_cvt_pk_bf16_f32 v85, v88, v89
	v_mfma_f32_32x32x16_bf16 v[98:113], v[196:199], v[150:153], v[98:113]
	v_exp_f32_e32 v74, v74
	v_exp_f32_e32 v75, v75
	v_add_f32_e32 v178, v178, v74
	v_add_f32_e32 v218, v218, v75
	v_cvt_pk_bf16_f32 v74, v74, v75
	v_mfma_f32_32x32x16_bf16 v[114:129], v[184:187], v[154:157], 0
	v_exp_f32_e32 v76, v76
	v_exp_f32_e32 v77, v77
	v_add_f32_e32 v219, v219, v76
	v_add_f32_e32 v220, v220, v77
	v_cvt_pk_bf16_f32 v75, v76, v77
	v_mfma_f32_32x32x16_bf16 v[114:129], v[188:191], v[138:141], v[114:129]
	v_exp_f32_e32 v78, v78
	v_exp_f32_e32 v79, v79
	v_add_f32_e32 v178, v178, v78
	v_add_f32_e32 v218, v218, v79
	v_cvt_pk_bf16_f32 v76, v78, v79
	v_mfma_f32_32x32x16_bf16 v[114:129], v[192:195], v[142:145], v[114:129]
	v_exp_f32_e32 v80, v80
	v_exp_f32_e32 v81, v81
	v_add_f32_e32 v219, v219, v80
	v_add_f32_e32 v220, v220, v81
	v_cvt_pk_bf16_f32 v77, v80, v81
	v_mfma_f32_32x32x16_bf16 v[114:129], v[196:199], v[158:161], v[114:129]
	v_exp_f32_e32 v90, v90
	v_exp_f32_e32 v91, v91
	v_add_f32_e32 v179, v179, v90
	v_add_f32_e32 v221, v221, v91
	v_cvt_pk_bf16_f32 v90, v90, v91
	s_waitcnt lgkmcnt(4)
	v_mfma_f32_32x32x16_bf16 v[50:65], v[200:203], v[66:69], v[50:65]
	ds_read_b128 v[184:187], v183 offset:36864
	ds_read_b128 v[188:191], v183 offset:36896
	ds_read_b128 v[192:195], v183 offset:36928
	ds_read_b128 v[196:199], v183 offset:36960
	v_exp_f32_e32 v92, v92
	v_exp_f32_e32 v93, v93
	v_add_f32_e32 v222, v222, v92
	v_add_f32_e32 v223, v223, v93
	v_cvt_pk_bf16_f32 v91, v92, v93
	v_mfma_f32_32x32x16_bf16 v[34:49], v[204:207], v[66:69], v[34:49]
	v_exp_f32_e32 v94, v94
	v_exp_f32_e32 v95, v95
	v_add_f32_e32 v179, v179, v94
	v_add_f32_e32 v221, v221, v95
	v_cvt_pk_bf16_f32 v92, v94, v95
	v_mfma_f32_32x32x16_bf16 v[18:33], v[200:203], v[82:85], v[18:33]
	v_exp_f32_e32 v96, v96
	v_exp_f32_e32 v97, v97
	v_add_f32_e32 v222, v222, v96
	v_add_f32_e32 v223, v223, v97
	v_cvt_pk_bf16_f32 v93, v96, v97
	v_mfma_f32_32x32x16_bf16 v[2:17], v[204:207], v[82:85], v[2:17]
	v_exp_f32_e32 v98, v98
	v_exp_f32_e32 v99, v99
	v_add_f32_e32 v178, v178, v98
	v_add_f32_e32 v218, v218, v99
	v_cvt_pk_bf16_f32 v98, v98, v99
	s_waitcnt lgkmcnt(4)
	v_mfma_f32_32x32x16_bf16 v[50:65], v[208:211], v[74:77], v[50:65]
	ds_read_b64_tr_b16 v[200:201], v216 offset:32256
	ds_read_b64_tr_b16 v[202:203], v216 offset:32832
	ds_read_b64_tr_b16 v[204:205], v216 offset:32320
	ds_read_b64_tr_b16 v[206:207], v216 offset:32896
	v_exp_f32_e32 v100, v100
	v_exp_f32_e32 v101, v101
	v_add_f32_e32 v219, v219, v100
	v_add_f32_e32 v220, v220, v101
	v_cvt_pk_bf16_f32 v99, v100, v101
	v_mfma_f32_32x32x16_bf16 v[34:49], v[212:215], v[74:77], v[34:49]
	v_exp_f32_e32 v102, v102
	v_exp_f32_e32 v103, v103
	v_add_f32_e32 v178, v178, v102
	v_add_f32_e32 v218, v218, v103
	v_cvt_pk_bf16_f32 v100, v102, v103
	v_mfma_f32_32x32x16_bf16 v[18:33], v[208:211], v[90:93], v[18:33]
	v_exp_f32_e32 v104, v104
	v_exp_f32_e32 v105, v105
	v_add_f32_e32 v219, v219, v104
	v_add_f32_e32 v220, v220, v105
	v_cvt_pk_bf16_f32 v101, v104, v105
	v_mfma_f32_32x32x16_bf16 v[2:17], v[212:215], v[90:93], v[2:17]
	v_exp_f32_e32 v114, v114
	v_exp_f32_e32 v115, v115
	v_add_f32_e32 v179, v179, v114
	v_add_f32_e32 v221, v221, v115
	v_cvt_pk_bf16_f32 v114, v114, v115
	s_waitcnt lgkmcnt(4)
	v_mfma_f32_32x32x16_bf16 v[66:81], v[184:187], v[130:133], 0
	ds_read_b64_tr_b16 v[208:209], v216 offset:34560
	ds_read_b64_tr_b16 v[210:211], v216 offset:35136
	ds_read_b64_tr_b16 v[212:213], v216 offset:34624
	ds_read_b64_tr_b16 v[214:215], v216 offset:35200
	v_exp_f32_e32 v116, v116
	v_exp_f32_e32 v117, v117
	v_add_f32_e32 v222, v222, v116
	v_add_f32_e32 v223, v223, v117
	v_cvt_pk_bf16_f32 v115, v116, v117
	v_mfma_f32_32x32x16_bf16 v[66:81], v[188:191], v[134:137], v[66:81]
	v_exp_f32_e32 v118, v118
	v_exp_f32_e32 v119, v119
	v_add_f32_e32 v179, v179, v118
	v_add_f32_e32 v221, v221, v119
	v_cvt_pk_bf16_f32 v116, v118, v119
	v_mfma_f32_32x32x16_bf16 v[66:81], v[192:195], v[146:149], v[66:81]
	v_exp_f32_e32 v120, v120
	v_exp_f32_e32 v121, v121
	v_add_f32_e32 v222, v222, v120
	v_add_f32_e32 v223, v223, v121
	v_cvt_pk_bf16_f32 v117, v120, v121
	v_mfma_f32_32x32x16_bf16 v[66:81], v[196:199], v[150:153], v[66:81]
	v_exp_f32_e32 v106, v106
	v_exp_f32_e32 v107, v107
	v_add_f32_e32 v178, v178, v106
	v_add_f32_e32 v218, v218, v107
	v_cvt_pk_bf16_f32 v106, v106, v107
	s_waitcnt lgkmcnt(4)
	v_mfma_f32_32x32x16_bf16 v[50:65], v[200:203], v[98:101], v[50:65]
	v_exp_f32_e32 v108, v108
	v_exp_f32_e32 v109, v109
	v_add_f32_e32 v219, v219, v108
	v_add_f32_e32 v220, v220, v109
	v_cvt_pk_bf16_f32 v107, v108, v109
	v_mfma_f32_32x32x16_bf16 v[34:49], v[204:207], v[98:101], v[34:49]
	v_exp_f32_e32 v110, v110
	v_exp_f32_e32 v111, v111
	v_add_f32_e32 v178, v178, v110
	v_add_f32_e32 v218, v218, v111
	v_cvt_pk_bf16_f32 v108, v110, v111
	v_mfma_f32_32x32x16_bf16 v[18:33], v[200:203], v[114:117], v[18:33]
	s_waitcnt vmcnt(0)
	ds_write_b128 v180, v[162:165]
	ds_write_b128 v180, v[166:169] offset:9216
	v_exp_f32_e32 v112, v112
	v_exp_f32_e32 v113, v113
	v_add_f32_e32 v219, v219, v112
	v_add_f32_e32 v220, v220, v113
	v_cvt_pk_bf16_f32 v109, v112, v113
	v_mfma_f32_32x32x16_bf16 v[2:17], v[204:207], v[114:117], v[2:17]
	v_exp_f32_e32 v122, v122
	v_exp_f32_e32 v123, v123
	v_add_f32_e32 v179, v179, v122
	v_add_f32_e32 v221, v221, v123
	v_cvt_pk_bf16_f32 v122, v122, v123
	v_mfma_f32_32x32x16_bf16 v[82:97], v[184:187], v[154:157], 0
	v_exp_f32_e32 v124, v124
	v_exp_f32_e32 v125, v125
	v_add_f32_e32 v222, v222, v124
	v_add_f32_e32 v223, v223, v125
	v_cvt_pk_bf16_f32 v123, v124, v125
	v_mfma_f32_32x32x16_bf16 v[82:97], v[188:191], v[138:141], v[82:97]
	v_exp_f32_e32 v126, v126
	v_exp_f32_e32 v127, v127
	v_add_f32_e32 v179, v179, v126
	v_add_f32_e32 v221, v221, v127
	v_cvt_pk_bf16_f32 v124, v126, v127
	v_mfma_f32_32x32x16_bf16 v[82:97], v[192:195], v[142:145], v[82:97]
	v_exp_f32_e32 v128, v128
	v_exp_f32_e32 v129, v129
	v_add_f32_e32 v222, v222, v128
	v_add_f32_e32 v223, v223, v129
	v_cvt_pk_bf16_f32 v125, v128, v129
	v_mfma_f32_32x32x16_bf16 v[82:97], v[196:199], v[158:161], v[82:97]
	s_waitcnt lgkmcnt(0)
	s_barrier
	ds_read_b128 v[184:187], v183 offset:41472
	ds_read_b128 v[188:191], v183 offset:41504
	ds_read_b128 v[192:195], v183 offset:41536
	ds_read_b128 v[196:199], v183 offset:41568
	v_exp_f32_e32 v66, v66
	v_exp_f32_e32 v67, v67
	v_add_f32_e32 v178, v178, v66
	v_add_f32_e32 v218, v218, v67
	v_cvt_pk_bf16_f32 v66, v66, v67
	v_mfma_f32_32x32x16_bf16 v[50:65], v[208:211], v[106:109], v[50:65]
	v_exp_f32_e32 v68, v68
	v_exp_f32_e32 v69, v69
	v_add_f32_e32 v219, v219, v68
	v_add_f32_e32 v220, v220, v69
	v_cvt_pk_bf16_f32 v67, v68, v69
	v_mfma_f32_32x32x16_bf16 v[34:49], v[212:215], v[106:109], v[34:49]
	v_exp_f32_e32 v70, v70
	v_exp_f32_e32 v71, v71
	v_add_f32_e32 v178, v178, v70
	v_add_f32_e32 v218, v218, v71
	v_cvt_pk_bf16_f32 v68, v70, v71
	v_mfma_f32_32x32x16_bf16 v[18:33], v[208:211], v[122:125], v[18:33]
	v_exp_f32_e32 v72, v72
	v_exp_f32_e32 v73, v73
	v_add_f32_e32 v219, v219, v72
	v_add_f32_e32 v220, v220, v73
	v_cvt_pk_bf16_f32 v69, v72, v73
	v_mfma_f32_32x32x16_bf16 v[2:17], v[212:215], v[122:125], v[2:17]
	v_exp_f32_e32 v82, v82
	v_exp_f32_e32 v83, v83
	v_add_f32_e32 v179, v179, v82
	v_add_f32_e32 v221, v221, v83
	v_cvt_pk_bf16_f32 v82, v82, v83
	s_waitcnt lgkmcnt(0)
	v_mfma_f32_32x32x16_bf16 v[98:113], v[184:187], v[130:133], 0
	ds_read_b64_tr_b16 v[200:201], v216 offset:46080
	ds_read_b64_tr_b16 v[202:203], v216 offset:46656
	ds_read_b64_tr_b16 v[204:205], v216 offset:46144
	ds_read_b64_tr_b16 v[206:207], v216 offset:46720
	v_exp_f32_e32 v84, v84
	v_exp_f32_e32 v85, v85
	v_add_f32_e32 v222, v222, v84
	v_add_f32_e32 v223, v223, v85
	v_cvt_pk_bf16_f32 v83, v84, v85
	v_mfma_f32_32x32x16_bf16 v[98:113], v[188:191], v[134:137], v[98:113]
	ds_read_b64_tr_b16 v[208:209], v216 offset:48384
	ds_read_b64_tr_b16 v[210:211], v216 offset:48960
	ds_read_b64_tr_b16 v[212:213], v216 offset:48448
	ds_read_b64_tr_b16 v[214:215], v216 offset:49024
	v_exp_f32_e32 v86, v86
	v_exp_f32_e32 v87, v87
	v_add_f32_e32 v179, v179, v86
	v_add_f32_e32 v221, v221, v87
	v_cvt_pk_bf16_f32 v84, v86, v87
	v_mfma_f32_32x32x16_bf16 v[98:113], v[192:195], v[146:149], v[98:113]
	v_exp_f32_e32 v88, v88
	v_exp_f32_e32 v89, v89
	v_add_f32_e32 v222, v222, v88
	v_add_f32_e32 v223, v223, v89
	v_cvt_pk_bf16_f32 v85, v88, v89
	v_mfma_f32_32x32x16_bf16 v[98:113], v[196:199], v[150:153], v[98:113]
	v_exp_f32_e32 v74, v74
	v_exp_f32_e32 v75, v75
	v_add_f32_e32 v178, v178, v74
	v_add_f32_e32 v218, v218, v75
	v_cvt_pk_bf16_f32 v74, v74, v75
	v_mfma_f32_32x32x16_bf16 v[114:129], v[184:187], v[154:157], 0
	v_exp_f32_e32 v76, v76
	v_exp_f32_e32 v77, v77
	v_add_f32_e32 v219, v219, v76
	v_add_f32_e32 v220, v220, v77
	v_cvt_pk_bf16_f32 v75, v76, v77
	v_mfma_f32_32x32x16_bf16 v[114:129], v[188:191], v[138:141], v[114:129]
	v_exp_f32_e32 v78, v78
	v_exp_f32_e32 v79, v79
	v_add_f32_e32 v178, v178, v78
	v_add_f32_e32 v218, v218, v79
	v_cvt_pk_bf16_f32 v76, v78, v79
	v_mfma_f32_32x32x16_bf16 v[114:129], v[192:195], v[142:145], v[114:129]
	v_exp_f32_e32 v80, v80
	v_exp_f32_e32 v81, v81
	v_add_f32_e32 v219, v219, v80
	v_add_f32_e32 v220, v220, v81
	v_cvt_pk_bf16_f32 v77, v80, v81
	v_mfma_f32_32x32x16_bf16 v[114:129], v[196:199], v[158:161], v[114:129]
	v_exp_f32_e32 v90, v90
	v_exp_f32_e32 v91, v91
	v_add_f32_e32 v179, v179, v90
	v_add_f32_e32 v221, v221, v91
	v_cvt_pk_bf16_f32 v90, v90, v91
	s_waitcnt lgkmcnt(4)
	v_mfma_f32_32x32x16_bf16 v[50:65], v[200:203], v[66:69], v[50:65]
	ds_read_b128 v[184:187], v183
	ds_read_b128 v[188:191], v183 offset:32
	ds_read_b128 v[192:195], v183 offset:64
	ds_read_b128 v[196:199], v183 offset:96
	v_exp_f32_e32 v92, v92
	v_exp_f32_e32 v93, v93
	v_add_f32_e32 v222, v222, v92
	v_add_f32_e32 v223, v223, v93
	v_cvt_pk_bf16_f32 v91, v92, v93
	v_mfma_f32_32x32x16_bf16 v[34:49], v[204:207], v[66:69], v[34:49]
	v_exp_f32_e32 v94, v94
	v_exp_f32_e32 v95, v95
	v_add_f32_e32 v179, v179, v94
	v_add_f32_e32 v221, v221, v95
	v_cvt_pk_bf16_f32 v92, v94, v95
	v_mfma_f32_32x32x16_bf16 v[18:33], v[200:203], v[82:85], v[18:33]
	v_exp_f32_e32 v96, v96
	v_exp_f32_e32 v97, v97
	v_add_f32_e32 v222, v222, v96
	v_add_f32_e32 v223, v223, v97
	v_cvt_pk_bf16_f32 v93, v96, v97
	v_mfma_f32_32x32x16_bf16 v[2:17], v[204:207], v[82:85], v[2:17]
	v_exp_f32_e32 v98, v98
	v_exp_f32_e32 v99, v99
	v_add_f32_e32 v178, v178, v98
	v_add_f32_e32 v218, v218, v99
	v_cvt_pk_bf16_f32 v98, v98, v99
	s_waitcnt lgkmcnt(4)
	v_mfma_f32_32x32x16_bf16 v[50:65], v[208:211], v[74:77], v[50:65]
	ds_read_b64_tr_b16 v[200:201], v216 offset:50688
	ds_read_b64_tr_b16 v[202:203], v216 offset:51264
	ds_read_b64_tr_b16 v[204:205], v216 offset:50752
	ds_read_b64_tr_b16 v[206:207], v216 offset:51328
	v_exp_f32_e32 v100, v100
	v_exp_f32_e32 v101, v101
	v_add_f32_e32 v219, v219, v100
	v_add_f32_e32 v220, v220, v101
	v_cvt_pk_bf16_f32 v99, v100, v101
	v_mfma_f32_32x32x16_bf16 v[34:49], v[212:215], v[74:77], v[34:49]
	v_exp_f32_e32 v102, v102
	v_exp_f32_e32 v103, v103
	v_add_f32_e32 v178, v178, v102
	v_add_f32_e32 v218, v218, v103
	v_cvt_pk_bf16_f32 v100, v102, v103
	v_mfma_f32_32x32x16_bf16 v[18:33], v[208:211], v[90:93], v[18:33]
	v_exp_f32_e32 v104, v104
	v_exp_f32_e32 v105, v105
	v_add_f32_e32 v219, v219, v104
	v_add_f32_e32 v220, v220, v105
	v_cvt_pk_bf16_f32 v101, v104, v105
	v_mfma_f32_32x32x16_bf16 v[2:17], v[212:215], v[90:93], v[2:17]
	v_exp_f32_e32 v114, v114
	v_exp_f32_e32 v115, v115
	v_add_f32_e32 v179, v179, v114
	v_add_f32_e32 v221, v221, v115
	v_cvt_pk_bf16_f32 v114, v114, v115
	s_waitcnt lgkmcnt(4)
	v_mfma_f32_32x32x16_bf16 v[66:81], v[184:187], v[130:133], 0
	ds_read_b64_tr_b16 v[208:209], v216 offset:52992
	ds_read_b64_tr_b16 v[210:211], v216 offset:53568
	ds_read_b64_tr_b16 v[212:213], v216 offset:53056
	ds_read_b64_tr_b16 v[214:215], v216 offset:53632
	v_exp_f32_e32 v116, v116
	v_exp_f32_e32 v117, v117
	v_add_f32_e32 v222, v222, v116
	v_add_f32_e32 v223, v223, v117
	v_cvt_pk_bf16_f32 v115, v116, v117
	v_mfma_f32_32x32x16_bf16 v[66:81], v[188:191], v[134:137], v[66:81]
	v_exp_f32_e32 v118, v118
	v_exp_f32_e32 v119, v119
	v_add_f32_e32 v179, v179, v118
	v_add_f32_e32 v221, v221, v119
	v_cvt_pk_bf16_f32 v116, v118, v119
	v_mfma_f32_32x32x16_bf16 v[66:81], v[192:195], v[146:149], v[66:81]
	v_exp_f32_e32 v120, v120
	v_exp_f32_e32 v121, v121
	v_add_f32_e32 v222, v222, v120
	v_add_f32_e32 v223, v223, v121
	v_cvt_pk_bf16_f32 v117, v120, v121
	v_mfma_f32_32x32x16_bf16 v[66:81], v[196:199], v[150:153], v[66:81]
	v_exp_f32_e32 v106, v106
	v_exp_f32_e32 v107, v107
	v_add_f32_e32 v178, v178, v106
	v_add_f32_e32 v218, v218, v107
	v_cvt_pk_bf16_f32 v106, v106, v107
	s_waitcnt lgkmcnt(4)
	v_mfma_f32_32x32x16_bf16 v[50:65], v[200:203], v[98:101], v[50:65]
	v_exp_f32_e32 v108, v108
	v_exp_f32_e32 v109, v109
	v_add_f32_e32 v219, v219, v108
	v_add_f32_e32 v220, v220, v109
	v_cvt_pk_bf16_f32 v107, v108, v109
	v_mfma_f32_32x32x16_bf16 v[34:49], v[204:207], v[98:101], v[34:49]
	v_exp_f32_e32 v110, v110
	v_exp_f32_e32 v111, v111
	v_add_f32_e32 v178, v178, v110
	v_add_f32_e32 v218, v218, v111
	v_cvt_pk_bf16_f32 v108, v110, v111
	v_mfma_f32_32x32x16_bf16 v[18:33], v[200:203], v[114:117], v[18:33]
	v_exp_f32_e32 v112, v112
	v_exp_f32_e32 v113, v113
	v_add_f32_e32 v219, v219, v112
	v_add_f32_e32 v220, v220, v113
	v_cvt_pk_bf16_f32 v109, v112, v113
	v_mfma_f32_32x32x16_bf16 v[2:17], v[204:207], v[114:117], v[2:17]
	v_exp_f32_e32 v122, v122
	v_exp_f32_e32 v123, v123
	v_add_f32_e32 v179, v179, v122
	v_add_f32_e32 v221, v221, v123
	v_cvt_pk_bf16_f32 v122, v122, v123
	v_mfma_f32_32x32x16_bf16 v[82:97], v[184:187], v[154:157], 0
	v_exp_f32_e32 v124, v124
	v_exp_f32_e32 v125, v125
	v_add_f32_e32 v222, v222, v124
	v_add_f32_e32 v223, v223, v125
	v_cvt_pk_bf16_f32 v123, v124, v125
	v_mfma_f32_32x32x16_bf16 v[82:97], v[188:191], v[138:141], v[82:97]
	v_exp_f32_e32 v126, v126
	v_exp_f32_e32 v127, v127
	v_add_f32_e32 v179, v179, v126
	v_add_f32_e32 v221, v221, v127
	v_cvt_pk_bf16_f32 v124, v126, v127
	v_mfma_f32_32x32x16_bf16 v[82:97], v[192:195], v[142:145], v[82:97]
	v_exp_f32_e32 v128, v128
	v_exp_f32_e32 v129, v129
	v_add_f32_e32 v222, v222, v128
	v_add_f32_e32 v223, v223, v129
	v_cvt_pk_bf16_f32 v125, v128, v129
	v_mfma_f32_32x32x16_bf16 v[82:97], v[196:199], v[158:161], v[82:97]
	s_waitcnt lgkmcnt(0)
	s_barrier
	ds_read_b128 v[184:187], v183 offset:4608
	ds_read_b128 v[188:191], v183 offset:4640
	ds_read_b128 v[192:195], v183 offset:4672
	ds_read_b128 v[196:199], v183 offset:4704
	v_exp_f32_e32 v66, v66
	v_exp_f32_e32 v67, v67
	v_add_f32_e32 v178, v178, v66
	v_add_f32_e32 v218, v218, v67
	v_cvt_pk_bf16_f32 v66, v66, v67
	v_mfma_f32_32x32x16_bf16 v[50:65], v[208:211], v[106:109], v[50:65]
	v_exp_f32_e32 v68, v68
	v_exp_f32_e32 v69, v69
	v_add_f32_e32 v219, v219, v68
	v_add_f32_e32 v220, v220, v69
	v_cvt_pk_bf16_f32 v67, v68, v69
	v_mfma_f32_32x32x16_bf16 v[34:49], v[212:215], v[106:109], v[34:49]
	v_exp_f32_e32 v70, v70
	v_exp_f32_e32 v71, v71
	v_add_f32_e32 v178, v178, v70
	v_add_f32_e32 v218, v218, v71
	v_cvt_pk_bf16_f32 v68, v70, v71
	v_mfma_f32_32x32x16_bf16 v[18:33], v[208:211], v[122:125], v[18:33]
	v_exp_f32_e32 v72, v72
	v_exp_f32_e32 v73, v73
	v_add_f32_e32 v219, v219, v72
	v_add_f32_e32 v220, v220, v73
	v_cvt_pk_bf16_f32 v69, v72, v73
	v_mfma_f32_32x32x16_bf16 v[2:17], v[212:215], v[122:125], v[2:17]
	v_exp_f32_e32 v82, v82
	v_exp_f32_e32 v83, v83
	v_add_f32_e32 v179, v179, v82
	v_add_f32_e32 v221, v221, v83
	v_cvt_pk_bf16_f32 v82, v82, v83
	s_waitcnt lgkmcnt(0)
	v_mfma_f32_32x32x16_bf16 v[98:113], v[184:187], v[130:133], 0
	ds_read_b64_tr_b16 v[200:201], v216 offset:9216
	ds_read_b64_tr_b16 v[202:203], v216 offset:9792
	ds_read_b64_tr_b16 v[204:205], v216 offset:9280
	ds_read_b64_tr_b16 v[206:207], v216 offset:9856
	v_exp_f32_e32 v84, v84
	v_exp_f32_e32 v85, v85
	v_add_f32_e32 v222, v222, v84
	v_add_f32_e32 v223, v223, v85
	v_cvt_pk_bf16_f32 v83, v84, v85
	v_mfma_f32_32x32x16_bf16 v[98:113], v[188:191], v[134:137], v[98:113]
	ds_read_b64_tr_b16 v[208:209], v216 offset:11520
	ds_read_b64_tr_b16 v[210:211], v216 offset:12096
	ds_read_b64_tr_b16 v[212:213], v216 offset:11584
	ds_read_b64_tr_b16 v[214:215], v216 offset:12160
	v_exp_f32_e32 v86, v86
	v_exp_f32_e32 v87, v87
	v_add_f32_e32 v179, v179, v86
	v_add_f32_e32 v221, v221, v87
	v_cvt_pk_bf16_f32 v84, v86, v87
	v_mfma_f32_32x32x16_bf16 v[98:113], v[192:195], v[146:149], v[98:113]
	v_exp_f32_e32 v88, v88
	v_exp_f32_e32 v89, v89
	v_add_f32_e32 v222, v222, v88
	v_add_f32_e32 v223, v223, v89
	v_cvt_pk_bf16_f32 v85, v88, v89
	v_mfma_f32_32x32x16_bf16 v[98:113], v[196:199], v[150:153], v[98:113]
	v_exp_f32_e32 v74, v74
	v_exp_f32_e32 v75, v75
	v_add_f32_e32 v178, v178, v74
	v_add_f32_e32 v218, v218, v75
	v_cvt_pk_bf16_f32 v74, v74, v75
	v_mfma_f32_32x32x16_bf16 v[114:129], v[184:187], v[154:157], 0
	v_exp_f32_e32 v76, v76
	v_exp_f32_e32 v77, v77
	v_add_f32_e32 v219, v219, v76
	v_add_f32_e32 v220, v220, v77
	v_cvt_pk_bf16_f32 v75, v76, v77
	v_mfma_f32_32x32x16_bf16 v[114:129], v[188:191], v[138:141], v[114:129]
	v_exp_f32_e32 v78, v78
	v_exp_f32_e32 v79, v79
	v_add_f32_e32 v178, v178, v78
	v_add_f32_e32 v218, v218, v79
	v_cvt_pk_bf16_f32 v76, v78, v79
	v_mfma_f32_32x32x16_bf16 v[114:129], v[192:195], v[142:145], v[114:129]
	v_exp_f32_e32 v80, v80
	v_exp_f32_e32 v81, v81
	v_add_f32_e32 v219, v219, v80
	v_add_f32_e32 v220, v220, v81
	v_cvt_pk_bf16_f32 v77, v80, v81
	v_mfma_f32_32x32x16_bf16 v[114:129], v[196:199], v[158:161], v[114:129]
	v_exp_f32_e32 v90, v90
	v_exp_f32_e32 v91, v91
	v_add_f32_e32 v179, v179, v90
	v_add_f32_e32 v221, v221, v91
	v_cvt_pk_bf16_f32 v90, v90, v91
	s_waitcnt lgkmcnt(4)
	v_mfma_f32_32x32x16_bf16 v[50:65], v[200:203], v[66:69], v[50:65]
	ds_read_b128 v[184:187], v183 offset:18432
	ds_read_b128 v[188:191], v183 offset:18464
	ds_read_b128 v[192:195], v183 offset:18496
	ds_read_b128 v[196:199], v183 offset:18528
	v_exp_f32_e32 v92, v92
	v_exp_f32_e32 v93, v93
	v_add_f32_e32 v222, v222, v92
	v_add_f32_e32 v223, v223, v93
	v_cvt_pk_bf16_f32 v91, v92, v93
	v_mfma_f32_32x32x16_bf16 v[34:49], v[204:207], v[66:69], v[34:49]
	v_exp_f32_e32 v94, v94
	v_exp_f32_e32 v95, v95
	v_add_f32_e32 v179, v179, v94
	v_add_f32_e32 v221, v221, v95
	v_cvt_pk_bf16_f32 v92, v94, v95
	v_mfma_f32_32x32x16_bf16 v[18:33], v[200:203], v[82:85], v[18:33]
	v_exp_f32_e32 v96, v96
	v_exp_f32_e32 v97, v97
	v_add_f32_e32 v222, v222, v96
	v_add_f32_e32 v223, v223, v97
	v_cvt_pk_bf16_f32 v93, v96, v97
	v_mfma_f32_32x32x16_bf16 v[2:17], v[204:207], v[82:85], v[2:17]
	v_exp_f32_e32 v98, v98
	v_exp_f32_e32 v99, v99
	v_add_f32_e32 v178, v178, v98
	v_add_f32_e32 v218, v218, v99
	v_cvt_pk_bf16_f32 v98, v98, v99
	s_waitcnt lgkmcnt(4)
	v_mfma_f32_32x32x16_bf16 v[50:65], v[208:211], v[74:77], v[50:65]
	ds_read_b64_tr_b16 v[200:201], v216 offset:13824
	ds_read_b64_tr_b16 v[202:203], v216 offset:14400
	ds_read_b64_tr_b16 v[204:205], v216 offset:13888
	ds_read_b64_tr_b16 v[206:207], v216 offset:14464
	v_exp_f32_e32 v100, v100
	v_exp_f32_e32 v101, v101
	v_add_f32_e32 v219, v219, v100
	v_add_f32_e32 v220, v220, v101
	v_cvt_pk_bf16_f32 v99, v100, v101
	v_mfma_f32_32x32x16_bf16 v[34:49], v[212:215], v[74:77], v[34:49]
	v_exp_f32_e32 v102, v102
	v_exp_f32_e32 v103, v103
	v_add_f32_e32 v178, v178, v102
	v_add_f32_e32 v218, v218, v103
	v_cvt_pk_bf16_f32 v100, v102, v103
	v_mfma_f32_32x32x16_bf16 v[18:33], v[208:211], v[90:93], v[18:33]
	v_exp_f32_e32 v104, v104
	v_exp_f32_e32 v105, v105
	v_add_f32_e32 v219, v219, v104
	v_add_f32_e32 v220, v220, v105
	v_cvt_pk_bf16_f32 v101, v104, v105
	v_mfma_f32_32x32x16_bf16 v[2:17], v[212:215], v[90:93], v[2:17]
	v_exp_f32_e32 v114, v114
	v_exp_f32_e32 v115, v115
	v_add_f32_e32 v179, v179, v114
	v_add_f32_e32 v221, v221, v115
	v_cvt_pk_bf16_f32 v114, v114, v115
	s_waitcnt lgkmcnt(4)
	v_mfma_f32_32x32x16_bf16 v[66:81], v[184:187], v[130:133], 0
	ds_read_b64_tr_b16 v[208:209], v216 offset:16128
	ds_read_b64_tr_b16 v[210:211], v216 offset:16704
	ds_read_b64_tr_b16 v[212:213], v216 offset:16192
	ds_read_b64_tr_b16 v[214:215], v216 offset:16768
	v_exp_f32_e32 v116, v116
	v_exp_f32_e32 v117, v117
	v_add_f32_e32 v222, v222, v116
	v_add_f32_e32 v223, v223, v117
	v_cvt_pk_bf16_f32 v115, v116, v117
	v_mfma_f32_32x32x16_bf16 v[66:81], v[188:191], v[134:137], v[66:81]
	v_exp_f32_e32 v118, v118
	v_exp_f32_e32 v119, v119
	v_add_f32_e32 v179, v179, v118
	v_add_f32_e32 v221, v221, v119
	v_cvt_pk_bf16_f32 v116, v118, v119
	v_mfma_f32_32x32x16_bf16 v[66:81], v[192:195], v[146:149], v[66:81]
	v_exp_f32_e32 v120, v120
	v_exp_f32_e32 v121, v121
	v_add_f32_e32 v222, v222, v120
	v_add_f32_e32 v223, v223, v121
	v_cvt_pk_bf16_f32 v117, v120, v121
	v_mfma_f32_32x32x16_bf16 v[66:81], v[196:199], v[150:153], v[66:81]
	v_exp_f32_e32 v106, v106
	v_exp_f32_e32 v107, v107
	v_add_f32_e32 v178, v178, v106
	v_add_f32_e32 v218, v218, v107
	v_cvt_pk_bf16_f32 v106, v106, v107
	s_waitcnt lgkmcnt(4)
	v_mfma_f32_32x32x16_bf16 v[50:65], v[200:203], v[98:101], v[50:65]
	v_exp_f32_e32 v108, v108
	v_exp_f32_e32 v109, v109
	v_add_f32_e32 v219, v219, v108
	v_add_f32_e32 v220, v220, v109
	v_cvt_pk_bf16_f32 v107, v108, v109
	v_mfma_f32_32x32x16_bf16 v[34:49], v[204:207], v[98:101], v[34:49]
	v_exp_f32_e32 v110, v110
	v_exp_f32_e32 v111, v111
	v_add_f32_e32 v178, v178, v110
	v_add_f32_e32 v218, v218, v111
	v_cvt_pk_bf16_f32 v108, v110, v111
	v_mfma_f32_32x32x16_bf16 v[18:33], v[200:203], v[114:117], v[18:33]
	v_exp_f32_e32 v112, v112
	v_exp_f32_e32 v113, v113
	v_add_f32_e32 v219, v219, v112
	v_add_f32_e32 v220, v220, v113
	v_cvt_pk_bf16_f32 v109, v112, v113
	v_mfma_f32_32x32x16_bf16 v[2:17], v[204:207], v[114:117], v[2:17]
	v_exp_f32_e32 v122, v122
	v_exp_f32_e32 v123, v123
	v_add_f32_e32 v179, v179, v122
	v_add_f32_e32 v221, v221, v123
	v_cvt_pk_bf16_f32 v122, v122, v123
	v_mfma_f32_32x32x16_bf16 v[82:97], v[184:187], v[154:157], 0
	v_exp_f32_e32 v124, v124
	v_exp_f32_e32 v125, v125
	v_add_f32_e32 v222, v222, v124
	v_add_f32_e32 v223, v223, v125
	v_cvt_pk_bf16_f32 v123, v124, v125
	v_mfma_f32_32x32x16_bf16 v[82:97], v[188:191], v[138:141], v[82:97]
	v_exp_f32_e32 v126, v126
	v_exp_f32_e32 v127, v127
	v_add_f32_e32 v179, v179, v126
	v_add_f32_e32 v221, v221, v127
	v_cvt_pk_bf16_f32 v124, v126, v127
	v_mfma_f32_32x32x16_bf16 v[82:97], v[192:195], v[142:145], v[82:97]
	v_exp_f32_e32 v128, v128
	v_exp_f32_e32 v129, v129
	v_add_f32_e32 v222, v222, v128
	v_add_f32_e32 v223, v223, v129
	v_cvt_pk_bf16_f32 v125, v128, v129
	v_mfma_f32_32x32x16_bf16 v[82:97], v[196:199], v[158:161], v[82:97]
	s_waitcnt lgkmcnt(0)
	v_mfma_f32_32x32x16_bf16 v[50:65], v[208:211], v[106:109], v[50:65]
	v_mfma_f32_32x32x16_bf16 v[34:49], v[212:215], v[106:109], v[34:49]
	v_mfma_f32_32x32x16_bf16 v[18:33], v[208:211], v[122:125], v[18:33]
	v_mfma_f32_32x32x16_bf16 v[2:17], v[212:215], v[122:125], v[2:17]
	v_add_f32_e32 v178, v178, v218
	v_add_f32_e32 v219, v219, v220
	v_add_f32_e32 v179, v179, v221
	v_add_f32_e32 v222, v222, v223
	v_add_f32_e32 v178, v178, v219
	v_add_f32_e32 v179, v179, v222
	s_branch .LBB0_299

.LBB0_517:
	s_add_u32 s24, s24, 0x30080
	s_addc_u32 s25, s25, 0
	s_add_u32 s61, s26, 0x100
	v_mov_b32_e32 v2, 0
	s_addc_u32 s62, s27, 0
	s_mov_b32 s63, -2
	v_mov_b32_e32 v3, v2
	v_mov_b32_e32 v4, v2
	v_mov_b32_e32 v5, v2
	v_mov_b32_e32 v6, v2
	v_mov_b32_e32 v7, v2
	v_mov_b32_e32 v8, v2
	v_mov_b32_e32 v9, v2
	v_mov_b32_e32 v10, v2
	v_mov_b32_e32 v11, v2
	v_mov_b32_e32 v12, v2
	v_mov_b32_e32 v13, v2
	v_mov_b32_e32 v14, v2
	v_mov_b32_e32 v15, v2
	v_mov_b32_e32 v16, v2
	v_mov_b32_e32 v17, v2
	s_nop 1
	v_mfma_f32_32x32x16_bf16 v[18:33], v[2:5], v[2:5], 0
	v_mfma_f32_32x32x16_bf16 v[34:49], v[2:5], v[2:5], 0
	v_mfma_f32_32x32x16_bf16 v[50:65], v[2:5], v[2:5], 0
	v_mfma_f32_32x32x16_bf16 v[66:81], v[2:5], v[2:5], 0
	v_mfma_f32_32x32x16_bf16 v[82:97], v[2:5], v[2:5], 0
	v_mfma_f32_32x32x16_bf16 v[98:113], v[2:5], v[2:5], 0
	v_mfma_f32_32x32x16_bf16 v[114:129], v[2:5], v[2:5], 0

.LBB0_652:
	s_ashr_i32 s23, s22, 31
	s_lshl_b64 s[24:25], s[22:23], 19
	s_add_u32 s24, s33, s24
	s_addc_u32 s25, s38, s25
	s_and_b64 s[26:27], s[0:1], exec
	s_cselect_b32 s23, s25, s31
	s_cselect_b32 s63, s24, s30
	s_ashr_i32 s21, s20, 31
	s_lshl_b64 s[26:27], s[20:21], 19
	s_add_u32 s26, s39, s26
	s_addc_u32 s27, s40, s27
	s_and_b64 s[36:37], s[0:1], exec
	s_cselect_b32 s21, s27, s35
	s_cselect_b32 s64, s26, s34
	s_add_u32 s30, s30, 0x40080
	s_addc_u32 s31, s31, 0
	s_add_u32 s65, s34, 0x100
	v_mov_b32_e32 v2, 0
	s_addc_u32 s66, s35, 0
	s_mov_b32 s67, -2
	v_mov_b32_e32 v3, v2
	v_mov_b32_e32 v4, v2
	v_mov_b32_e32 v5, v2
	v_mov_b32_e32 v6, v2
	v_mov_b32_e32 v7, v2
	v_mov_b32_e32 v8, v2
	v_mov_b32_e32 v9, v2
	v_mov_b32_e32 v10, v2
	v_mov_b32_e32 v11, v2
	v_mov_b32_e32 v12, v2
	v_mov_b32_e32 v13, v2
	v_mov_b32_e32 v14, v2
	v_mov_b32_e32 v15, v2
	v_mov_b32_e32 v16, v2
	v_mov_b32_e32 v17, v2
	s_nop 1
	v_mfma_f32_32x32x16_bf16 v[18:33], v[2:5], v[2:5], 0
	v_mfma_f32_32x32x16_bf16 v[34:49], v[2:5], v[2:5], 0
	v_mfma_f32_32x32x16_bf16 v[50:65], v[2:5], v[2:5], 0
	v_mfma_f32_32x32x16_bf16 v[66:81], v[2:5], v[2:5], 0
	v_mfma_f32_32x32x16_bf16 v[82:97], v[2:5], v[2:5], 0
	v_mfma_f32_32x32x16_bf16 v[98:113], v[2:5], v[2:5], 0
	v_mfma_f32_32x32x16_bf16 v[114:129], v[2:5], v[2:5], 0

.LBB0_727:
	s_ashr_i32 s23, s22, 31
	s_lshl_b64 s[24:25], s[22:23], 21
	s_add_u32 s24, s33, s24
	s_addc_u32 s25, s38, s25
	s_and_b64 s[26:27], s[0:1], exec
	s_cselect_b32 s23, s25, s31
	s_cselect_b32 s63, s24, s30
	s_ashr_i32 s21, s20, 31
	s_lshl_b64 s[26:27], s[20:21], 21
	s_add_u32 s26, s39, s26
	s_addc_u32 s27, s40, s27
	s_and_b64 s[36:37], s[0:1], exec
	s_cselect_b32 s21, s27, s35
	s_cselect_b32 s64, s26, s34
	s_add_u32 s30, s30, 0x100080
	s_addc_u32 s31, s31, 0
	s_add_u32 s65, s34, 0x100
	v_mov_b32_e32 v2, 0
	s_addc_u32 s66, s35, 0
	s_mov_b32 s67, -2
	v_mov_b32_e32 v3, v2
	v_mov_b32_e32 v4, v2
	v_mov_b32_e32 v5, v2
	v_mov_b32_e32 v6, v2
	v_mov_b32_e32 v7, v2
	v_mov_b32_e32 v8, v2
	v_mov_b32_e32 v9, v2
	v_mov_b32_e32 v10, v2
	v_mov_b32_e32 v11, v2
	v_mov_b32_e32 v12, v2
	v_mov_b32_e32 v13, v2
	v_mov_b32_e32 v14, v2
	v_mov_b32_e32 v15, v2
	v_mov_b32_e32 v16, v2
	v_mov_b32_e32 v17, v2
	s_nop 1
	v_mfma_f32_32x32x16_bf16 v[18:33], v[2:5], v[2:5], 0
	v_mfma_f32_32x32x16_bf16 v[34:49], v[2:5], v[2:5], 0
	v_mfma_f32_32x32x16_bf16 v[50:65], v[2:5], v[2:5], 0
	v_mfma_f32_32x32x16_bf16 v[66:81], v[2:5], v[2:5], 0
	v_mfma_f32_32x32x16_bf16 v[82:97], v[2:5], v[2:5], 0
	v_mfma_f32_32x32x16_bf16 v[98:113], v[2:5], v[2:5], 0
	v_mfma_f32_32x32x16_bf16 v[114:129], v[2:5], v[2:5], 0

.LBB0_854:
	s_ashr_i32 s15, s14, 31
	s_lshl_b64 s[16:17], s[14:15], 19
	s_add_u32 s16, s3, s16
	s_addc_u32 s17, s28, s17
	s_and_b64 s[18:19], s[0:1], exec
	s_cselect_b32 s15, s17, s23
	s_cselect_b32 s53, s16, s22
	s_ashr_i32 s13, s12, 31
	s_lshl_b64 s[18:19], s[12:13], 19
	s_add_u32 s18, s29, s18
	s_addc_u32 s19, s30, s19
	s_and_b64 s[26:27], s[0:1], exec
	s_cselect_b32 s13, s19, s25
	s_cselect_b32 s54, s18, s24
	s_add_u32 s22, s22, 0x40080
	s_addc_u32 s23, s23, 0
	s_add_u32 s55, s24, 0x100
	v_mov_b32_e32 v2, 0
	s_addc_u32 s56, s25, 0
	s_mov_b32 s57, -2
	v_mov_b32_e32 v3, v2
	v_mov_b32_e32 v4, v2
	v_mov_b32_e32 v5, v2
	v_mov_b32_e32 v6, v2
	v_mov_b32_e32 v7, v2
	v_mov_b32_e32 v8, v2
	v_mov_b32_e32 v9, v2
	v_mov_b32_e32 v10, v2
	v_mov_b32_e32 v11, v2
	v_mov_b32_e32 v12, v2
	v_mov_b32_e32 v13, v2
	v_mov_b32_e32 v14, v2
	v_mov_b32_e32 v15, v2
	v_mov_b32_e32 v16, v2
	v_mov_b32_e32 v17, v2
	s_nop 1
	v_mfma_f32_32x32x16_bf16 v[18:33], v[2:5], v[2:5], 0
	v_mfma_f32_32x32x16_bf16 v[34:49], v[2:5], v[2:5], 0
	v_mfma_f32_32x32x16_bf16 v[50:65], v[2:5], v[2:5], 0
	v_mfma_f32_32x32x16_bf16 v[66:81], v[2:5], v[2:5], 0
	v_mfma_f32_32x32x16_bf16 v[82:97], v[2:5], v[2:5], 0
	v_mfma_f32_32x32x16_bf16 v[98:113], v[2:5], v[2:5], 0
	v_mfma_f32_32x32x16_bf16 v[114:129], v[2:5], v[2:5], 0

.LBB0_1030:
	s_ashr_i32 s23, s22, 31
	s_lshl_b64 s[24:25], s[22:23], 19
	s_add_u32 s24, s33, s24
	s_addc_u32 s25, s38, s25
	s_and_b64 s[26:27], s[0:1], exec
	s_cselect_b32 s23, s25, s31
	s_cselect_b32 s61, s24, s30
	s_ashr_i32 s21, s20, 31
	s_lshl_b64 s[26:27], s[20:21], 19
	s_add_u32 s26, s39, s26
	s_addc_u32 s27, s40, s27
	s_and_b64 s[36:37], s[0:1], exec
	s_cselect_b32 s21, s27, s35
	s_cselect_b32 s62, s26, s34
	s_add_u32 s30, s30, 0x40080
	s_addc_u32 s31, s31, 0
	s_add_u32 s63, s34, 0x100
	v_mov_b32_e32 v2, 0
	s_addc_u32 s64, s35, 0
	s_mov_b32 s65, -2
	v_mov_b32_e32 v3, v2
	v_mov_b32_e32 v4, v2
	v_mov_b32_e32 v5, v2
	v_mov_b32_e32 v6, v2
	v_mov_b32_e32 v7, v2
	v_mov_b32_e32 v8, v2
	v_mov_b32_e32 v9, v2
	v_mov_b32_e32 v10, v2
	v_mov_b32_e32 v11, v2
	v_mov_b32_e32 v12, v2
	v_mov_b32_e32 v13, v2
	v_mov_b32_e32 v14, v2
	v_mov_b32_e32 v15, v2
	v_mov_b32_e32 v16, v2
	v_mov_b32_e32 v17, v2
	s_nop 1
	v_mfma_f32_32x32x16_bf16 v[18:33], v[2:5], v[2:5], 0
	v_mfma_f32_32x32x16_bf16 v[34:49], v[2:5], v[2:5], 0
	v_mfma_f32_32x32x16_bf16 v[50:65], v[2:5], v[2:5], 0
	v_mfma_f32_32x32x16_bf16 v[66:81], v[2:5], v[2:5], 0
	v_mfma_f32_32x32x16_bf16 v[82:97], v[2:5], v[2:5], 0
	v_mfma_f32_32x32x16_bf16 v[98:113], v[2:5], v[2:5], 0
	v_mfma_f32_32x32x16_bf16 v[114:129], v[2:5], v[2:5], 0

.LBB0_1240:
	s_ashr_i32 s23, s22, 31
	s_lshl_b64 s[24:25], s[22:23], 21
	s_add_u32 s24, s33, s24
	s_addc_u32 s25, s38, s25
	s_and_b64 s[26:27], s[0:1], exec
	s_cselect_b32 s23, s25, s31
	s_cselect_b32 s61, s24, s30
	s_ashr_i32 s21, s20, 31
	s_lshl_b64 s[26:27], s[20:21], 21
	s_add_u32 s26, s39, s26
	s_addc_u32 s27, s40, s27
	s_and_b64 s[36:37], s[0:1], exec
	s_cselect_b32 s21, s27, s35
	s_cselect_b32 s62, s26, s34
	s_add_u32 s30, s30, 0x100080
	s_addc_u32 s31, s31, 0
	s_add_u32 s63, s34, 0x100
	v_mov_b32_e32 v2, 0
	s_addc_u32 s64, s35, 0
	s_mov_b32 s65, -2
	v_mov_b32_e32 v3, v2
	v_mov_b32_e32 v4, v2
	v_mov_b32_e32 v5, v2
	v_mov_b32_e32 v6, v2
	v_mov_b32_e32 v7, v2
	v_mov_b32_e32 v8, v2
	v_mov_b32_e32 v9, v2
	v_mov_b32_e32 v10, v2
	v_mov_b32_e32 v11, v2
	v_mov_b32_e32 v12, v2
	v_mov_b32_e32 v13, v2
	v_mov_b32_e32 v14, v2
	v_mov_b32_e32 v15, v2
	v_mov_b32_e32 v16, v2
	v_mov_b32_e32 v17, v2
	s_nop 1
	v_mfma_f32_32x32x16_bf16 v[18:33], v[2:5], v[2:5], 0
	v_mfma_f32_32x32x16_bf16 v[34:49], v[2:5], v[2:5], 0
	v_mfma_f32_32x32x16_bf16 v[50:65], v[2:5], v[2:5], 0
	v_mfma_f32_32x32x16_bf16 v[66:81], v[2:5], v[2:5], 0
	v_mfma_f32_32x32x16_bf16 v[82:97], v[2:5], v[2:5], 0
	v_mfma_f32_32x32x16_bf16 v[98:113], v[2:5], v[2:5], 0
	v_mfma_f32_32x32x16_bf16 v[114:129], v[2:5], v[2:5], 0
